# weight conversion read-out: 8 transposed LDS reads in flight with counted lgkmcnt instead of one read per wait; global stores
# baseline (speedup 1.0000x reference)
; #define LAS __attribute__((address_space(3)))
; __device__ __forceinline__ unsigned cvt_pk_bf16(float lo, float hi) { unsigned r; asm volatile("v_cvt_pk_bf16_f32 %0, %1, %2" : "=v"(r) : "v"(lo), "v"(hi)); return r; }
; #define LDS_WAIT() asm volatile("s_waitcnt lgkmcnt(0)" ::: "memory")
; __device__ __forceinline__ void tr_item(const float* __restrict__ W, int K, int N, bf16_t* __restrict__ WT, int dst_row0, int src_col0, int k0, LAS float* scr, int lane) {
;     ...
;     const int c = lane & 7;
; #pragma unroll
;     for (int j = 0; j < 4; ++j) { const int n = (lane >> 3) + 8 * j; const LAS float* s = scr + (8 * c) * 33 + n;
;         u32x4 o; o.x = cvt_pk_bf16(s[0 * 33], s[1 * 33]); o.y = cvt_pk_bf16(s[2 * 33], s[3 * 33]); o.z = cvt_pk_bf16(s[4 * 33], s[5 * 33]); o.w = cvt_pk_bf16(s[6 * 33], s[7 * 33]);
;         *(u32x4*)(WT + (size_t)(dst_row0 + n) * K + k0 + 8 * c) = o; }
;     LDS_WAIT(); asm volatile("" ::: "memory");
.LBB0_208:
	s_waitcnt lgkmcnt(0)
	ds_read2_b32 v[36:37], v25 offset1:33
	ds_read2_b32 v[38:39], v25 offset0:66 offset1:99
	ds_read2_b32 v[40:41], v25 offset0:132 offset1:165
	ds_read2_b32 v[42:43], v25 offset0:198 offset1:231
	ds_read2_b32 v[44:45], v25 offset0:8 offset1:41
	ds_read2_b32 v[46:47], v25 offset0:74 offset1:107
	ds_read2_b32 v[48:49], v25 offset0:140 offset1:173
	ds_read2_b32 v[50:51], v25 offset0:206 offset1:239
	s_waitcnt lgkmcnt(7)
	v_cvt_pk_bf16_f32 v30, v36, v37
	s_ashr_i32 s37, s36, 31
	s_waitcnt lgkmcnt(6)
	v_cvt_pk_bf16_f32 v31, v38, v39
	v_lshl_add_u64 v[22:23], s[36:37], 1, v[6:7]
	s_waitcnt lgkmcnt(5)
	v_cvt_pk_bf16_f32 v32, v40, v41
	v_add_u32_e32 v29, s8, v24
	s_movk_i32 s4, 0x2c00
	s_waitcnt lgkmcnt(4)
	v_cvt_pk_bf16_f32 v33, v42, v43
	v_mad_i64_i32 v[34:35], s[28:29], v29, s4, v[22:23]
	global_store_dwordx4 v[34:35], v[30:33], off
	s_nop 1
	v_add_u32_e32 v29, s8, v26
	s_waitcnt lgkmcnt(3)
	v_cvt_pk_bf16_f32 v30, v44, v45
	s_waitcnt lgkmcnt(2)
	v_cvt_pk_bf16_f32 v31, v46, v47
	s_waitcnt lgkmcnt(1)
	v_cvt_pk_bf16_f32 v32, v48, v49
	s_waitcnt lgkmcnt(0)
	v_cvt_pk_bf16_f32 v33, v50, v51
	v_mad_i64_i32 v[34:35], s[28:29], v29, s4, v[22:23]
	global_store_dwordx4 v[34:35], v[30:33], off
	s_nop 1
	ds_read2_b32 v[36:37], v25 offset0:16 offset1:49
	ds_read2_b32 v[38:39], v25 offset0:82 offset1:115
	ds_read2_b32 v[40:41], v25 offset0:148 offset1:181
	ds_read2_b32 v[42:43], v25 offset0:214 offset1:247
	ds_read2_b32 v[44:45], v25 offset0:24 offset1:57
	ds_read2_b32 v[46:47], v25 offset0:90 offset1:123
	ds_read2_b32 v[48:49], v25 offset0:156 offset1:189
	ds_read2_b32 v[50:51], v25 offset0:222 offset1:255
	v_add_u32_e32 v29, s8, v27
	s_waitcnt lgkmcnt(7)
	v_cvt_pk_bf16_f32 v30, v36, v37
	s_waitcnt lgkmcnt(6)
	v_cvt_pk_bf16_f32 v31, v38, v39
	s_waitcnt lgkmcnt(5)
	v_cvt_pk_bf16_f32 v32, v40, v41
	s_waitcnt lgkmcnt(4)
	v_cvt_pk_bf16_f32 v33, v42, v43
	v_mad_i64_i32 v[34:35], s[28:29], v29, s4, v[22:23]
	global_store_dwordx4 v[34:35], v[30:33], off
	s_nop 1
	v_add_u32_e32 v29, s8, v28
	s_waitcnt lgkmcnt(3)
	v_cvt_pk_bf16_f32 v30, v44, v45
	s_waitcnt lgkmcnt(2)
	v_cvt_pk_bf16_f32 v31, v46, v47
	v_mad_i64_i32 v[22:23], s[8:9], v29, s4, v[22:23]
	s_waitcnt lgkmcnt(1)
	v_cvt_pk_bf16_f32 v32, v48, v49
	s_waitcnt lgkmcnt(0)
	v_cvt_pk_bf16_f32 v33, v50, v51
	global_store_dwordx4 v[22:23], v[30:33], off
	s_nop 1
	s_waitcnt lgkmcnt(0)

; #define LAS __attribute__((address_space(3)))
; __device__ __forceinline__ unsigned cvt_pk_bf16(float lo, float hi) { unsigned r; asm volatile("v_cvt_pk_bf16_f32 %0, %1, %2" : "=v"(r) : "v"(lo), "v"(hi)); return r; }
; #define LDS_WAIT() asm volatile("s_waitcnt lgkmcnt(0)" ::: "memory")
; __device__ __forceinline__ void tr_item(const float* __restrict__ W, int K, int N, bf16_t* __restrict__ WT, int dst_row0, int src_col0, int k0, LAS float* scr, int lane) {
;     ...
;     const int c = lane & 7;
; #pragma unroll
;     for (int j = 0; j < 4; ++j) { const int n = (lane >> 3) + 8 * j; const LAS float* s = scr + (8 * c) * 33 + n;
;         u32x4 o; o.x = cvt_pk_bf16(s[0 * 33], s[1 * 33]); o.y = cvt_pk_bf16(s[2 * 33], s[3 * 33]); o.z = cvt_pk_bf16(s[4 * 33], s[5 * 33]); o.w = cvt_pk_bf16(s[6 * 33], s[7 * 33]);
;         *(u32x4*)(WT + (size_t)(dst_row0 + n) * K + k0 + 8 * c) = o; }
;     LDS_WAIT(); asm volatile("" ::: "memory");
.LBB0_217:
	s_waitcnt lgkmcnt(0)
	ds_read2_b32 v[36:37], v25 offset1:33
	ds_read2_b32 v[38:39], v25 offset0:66 offset1:99
	ds_read2_b32 v[40:41], v25 offset0:132 offset1:165
	ds_read2_b32 v[42:43], v25 offset0:198 offset1:231
	ds_read2_b32 v[44:45], v25 offset0:8 offset1:41
	ds_read2_b32 v[46:47], v25 offset0:74 offset1:107
	ds_read2_b32 v[48:49], v25 offset0:140 offset1:173
	ds_read2_b32 v[50:51], v25 offset0:206 offset1:239
	s_waitcnt lgkmcnt(7)
	v_cvt_pk_bf16_f32 v30, v36, v37
	s_waitcnt lgkmcnt(6)
	v_cvt_pk_bf16_f32 v31, v38, v39
	s_waitcnt lgkmcnt(5)
	v_cvt_pk_bf16_f32 v32, v40, v41
	s_waitcnt lgkmcnt(4)
	v_cvt_pk_bf16_f32 v33, v42, v43
	v_add_u32_e32 v34, s36, v24
	s_ashr_i32 s39, s38, 31
	v_ashrrev_i32_e32 v35, 31, v34
	v_lshl_add_u64 v[22:23], s[38:39], 1, v[4:5]
	v_lshlrev_b64 v[34:35], 12, v[34:35]
	v_lshl_add_u64 v[34:35], v[22:23], 0, v[34:35]
	global_store_dwordx4 v[34:35], v[30:33], off
	s_nop 1
	s_waitcnt lgkmcnt(3)
	v_cvt_pk_bf16_f32 v30, v44, v45
	s_waitcnt lgkmcnt(2)
	v_cvt_pk_bf16_f32 v31, v46, v47
	s_waitcnt lgkmcnt(1)
	v_cvt_pk_bf16_f32 v32, v48, v49
	s_waitcnt lgkmcnt(0)
	v_cvt_pk_bf16_f32 v33, v50, v51
	v_add_u32_e32 v34, s36, v26
	v_ashrrev_i32_e32 v35, 31, v34
	v_lshlrev_b64 v[34:35], 12, v[34:35]
	v_lshl_add_u64 v[34:35], v[22:23], 0, v[34:35]
	global_store_dwordx4 v[34:35], v[30:33], off
	s_nop 1
	ds_read2_b32 v[36:37], v25 offset0:16 offset1:49
	ds_read2_b32 v[38:39], v25 offset0:82 offset1:115
	ds_read2_b32 v[40:41], v25 offset0:148 offset1:181
	ds_read2_b32 v[42:43], v25 offset0:214 offset1:247
	ds_read2_b32 v[44:45], v25 offset0:24 offset1:57
	ds_read2_b32 v[46:47], v25 offset0:90 offset1:123
	ds_read2_b32 v[48:49], v25 offset0:156 offset1:189
	ds_read2_b32 v[50:51], v25 offset0:222 offset1:255
	s_waitcnt lgkmcnt(7)
	v_cvt_pk_bf16_f32 v30, v36, v37
	s_waitcnt lgkmcnt(6)
	v_cvt_pk_bf16_f32 v31, v38, v39
	s_waitcnt lgkmcnt(5)
	v_cvt_pk_bf16_f32 v32, v40, v41
	s_waitcnt lgkmcnt(4)
	v_cvt_pk_bf16_f32 v33, v42, v43
	v_add_u32_e32 v34, s36, v27
	v_ashrrev_i32_e32 v35, 31, v34
	v_lshlrev_b64 v[34:35], 12, v[34:35]
	v_lshl_add_u64 v[34:35], v[22:23], 0, v[34:35]
	global_store_dwordx4 v[34:35], v[30:33], off
	s_nop 1
	s_waitcnt lgkmcnt(3)
	v_cvt_pk_bf16_f32 v30, v44, v45
	s_waitcnt lgkmcnt(2)
	v_cvt_pk_bf16_f32 v31, v46, v47
	s_waitcnt lgkmcnt(1)
	v_cvt_pk_bf16_f32 v32, v48, v49
	s_waitcnt lgkmcnt(0)
	v_cvt_pk_bf16_f32 v33, v50, v51
	v_add_u32_e32 v34, s36, v28
	v_ashrrev_i32_e32 v35, 31, v34
	v_lshlrev_b64 v[34:35], 12, v[34:35]
	v_lshl_add_u64 v[22:23], v[22:23], 0, v[34:35]
	global_store_dwordx4 v[22:23], v[30:33], off
	s_nop 1
	s_waitcnt lgkmcnt(0)
	s_mov_b64 s[36:37], 0

; #define LAS __attribute__((address_space(3)))
; __device__ __forceinline__ unsigned cvt_pk_bf16(float lo, float hi) { unsigned r; asm volatile("v_cvt_pk_bf16_f32 %0, %1, %2" : "=v"(r) : "v"(lo), "v"(hi)); return r; }
; #define LDS_WAIT() asm volatile("s_waitcnt lgkmcnt(0)" ::: "memory")
; __device__ __forceinline__ void tr_item(const float* __restrict__ W, int K, int N, bf16_t* __restrict__ WT, int dst_row0, int src_col0, int k0, LAS float* scr, int lane) {
;     ...
;     const int c = lane & 7;
; #pragma unroll
;     for (int j = 0; j < 4; ++j) { const int n = (lane >> 3) + 8 * j; const LAS float* s = scr + (8 * c) * 33 + n;
;         u32x4 o; o.x = cvt_pk_bf16(s[0 * 33], s[1 * 33]); o.y = cvt_pk_bf16(s[2 * 33], s[3 * 33]); o.z = cvt_pk_bf16(s[4 * 33], s[5 * 33]); o.w = cvt_pk_bf16(s[6 * 33], s[7 * 33]);
;         *(u32x4*)(WT + (size_t)(dst_row0 + n) * K + k0 + 8 * c) = o; }
;     LDS_WAIT(); asm volatile("" ::: "memory");
.LBB0_877:
	s_waitcnt lgkmcnt(0)
	v_add_u32_e32 v44, s7, v31
	ds_read2_b32 v[56:57], v33 offset1:33
	ds_read2_b32 v[60:61], v33 offset0:66 offset1:99
	ds_read2_b32 v[62:63], v33 offset0:132 offset1:165
	ds_read2_b32 v[64:65], v33 offset0:198 offset1:231
	ds_read2_b32 v[66:67], v33 offset0:8 offset1:41
	ds_read2_b32 v[68:69], v33 offset0:74 offset1:107
	ds_read2_b32 v[70:71], v33 offset0:140 offset1:173
	ds_read2_b32 v[72:73], v33 offset0:206 offset1:239
	s_ashr_i32 s41, s40, 31
	v_ashrrev_i32_e32 v45, 31, v44
	s_waitcnt lgkmcnt(7)
	v_cvt_pk_bf16_f32 v38, v56, v57
	v_lshl_add_u64 v[46:47], s[40:41], 1, v[10:11]
	v_lshlrev_b64 v[44:45], 12, v[44:45]
	s_waitcnt lgkmcnt(6)
	v_cvt_pk_bf16_f32 v39, v60, v61
	v_lshl_add_u64 v[44:45], v[46:47], 0, v[44:45]
	s_waitcnt lgkmcnt(5)
	v_cvt_pk_bf16_f32 v40, v62, v63
	s_waitcnt lgkmcnt(4)
	v_cvt_pk_bf16_f32 v41, v64, v65
	global_store_dwordx4 v[44:45], v[38:41], off
	s_nop 1
	v_add_u32_e32 v44, s7, v35
	v_ashrrev_i32_e32 v45, 31, v44
	s_waitcnt lgkmcnt(3)
	v_cvt_pk_bf16_f32 v38, v66, v67
	v_lshlrev_b64 v[44:45], 12, v[44:45]
	s_waitcnt lgkmcnt(2)
	v_cvt_pk_bf16_f32 v39, v68, v69
	v_lshl_add_u64 v[44:45], v[46:47], 0, v[44:45]
	s_waitcnt lgkmcnt(1)
	v_cvt_pk_bf16_f32 v40, v70, v71
	s_waitcnt lgkmcnt(0)
	v_cvt_pk_bf16_f32 v41, v72, v73
	global_store_dwordx4 v[44:45], v[38:41], off
	s_nop 1
	v_add_u32_e32 v44, s7, v36
	ds_read2_b32 v[56:57], v33 offset0:16 offset1:49
	ds_read2_b32 v[60:61], v33 offset0:82 offset1:115
	ds_read2_b32 v[62:63], v33 offset0:148 offset1:181
	ds_read2_b32 v[64:65], v33 offset0:214 offset1:247
	ds_read2_b32 v[66:67], v33 offset0:24 offset1:57
	ds_read2_b32 v[68:69], v33 offset0:90 offset1:123
	ds_read2_b32 v[70:71], v33 offset0:156 offset1:189
	ds_read2_b32 v[72:73], v33 offset0:222 offset1:255
	s_waitcnt lgkmcnt(7)
	v_cvt_pk_bf16_f32 v38, v56, v57
	v_ashrrev_i32_e32 v45, 31, v44
	s_waitcnt lgkmcnt(6)
	v_cvt_pk_bf16_f32 v39, v60, v61
	v_lshlrev_b64 v[44:45], 12, v[44:45]
	s_waitcnt lgkmcnt(5)
	v_cvt_pk_bf16_f32 v40, v62, v63
	s_waitcnt lgkmcnt(4)
	v_cvt_pk_bf16_f32 v41, v64, v65
	v_lshl_add_u64 v[44:45], v[46:47], 0, v[44:45]
	global_store_dwordx4 v[44:45], v[38:41], off
	s_nop 1
	v_add_u32_e32 v44, s7, v37
	v_ashrrev_i32_e32 v45, 31, v44
	s_waitcnt lgkmcnt(3)
	v_cvt_pk_bf16_f32 v38, v66, v67
	s_waitcnt lgkmcnt(2)
	v_cvt_pk_bf16_f32 v39, v68, v69
	s_waitcnt lgkmcnt(1)
	v_cvt_pk_bf16_f32 v40, v70, v71
	v_lshlrev_b64 v[44:45], 12, v[44:45]
	s_waitcnt lgkmcnt(0)
	v_cvt_pk_bf16_f32 v41, v72, v73
	v_lshl_add_u64 v[42:43], v[46:47], 0, v[44:45]
	global_store_dwordx4 v[42:43], v[38:41], off
	s_nop 1
	s_waitcnt lgkmcnt(0)

; #define LAS __attribute__((address_space(3)))
; __device__ __forceinline__ unsigned cvt_pk_bf16(float lo, float hi) { unsigned r; asm volatile("v_cvt_pk_bf16_f32 %0, %1, %2" : "=v"(r) : "v"(lo), "v"(hi)); return r; }
; #define LDS_WAIT() asm volatile("s_waitcnt lgkmcnt(0)" ::: "memory")
; __device__ __forceinline__ void tr_item(const float* __restrict__ W, int K, int N, bf16_t* __restrict__ WT, int dst_row0, int src_col0, int k0, LAS float* scr, int lane) {
;     ...
;     const int c = lane & 7;
; #pragma unroll
;     for (int j = 0; j < 4; ++j) { const int n = (lane >> 3) + 8 * j; const LAS float* s = scr + (8 * c) * 33 + n;
;         u32x4 o; o.x = cvt_pk_bf16(s[0 * 33], s[1 * 33]); o.y = cvt_pk_bf16(s[2 * 33], s[3 * 33]); o.z = cvt_pk_bf16(s[4 * 33], s[5 * 33]); o.w = cvt_pk_bf16(s[6 * 33], s[7 * 33]);
;         *(u32x4*)(WT + (size_t)(dst_row0 + n) * K + k0 + 8 * c) = o; }
;     LDS_WAIT(); asm volatile("" ::: "memory");
.LBB0_891:
	s_waitcnt lgkmcnt(0)
	ds_read2_b32 v[56:57], v33 offset1:33
	ds_read2_b32 v[60:61], v33 offset0:66 offset1:99
	ds_read2_b32 v[62:63], v33 offset0:132 offset1:165
	ds_read2_b32 v[64:65], v33 offset0:198 offset1:231
	ds_read2_b32 v[66:67], v33 offset0:8 offset1:41
	ds_read2_b32 v[68:69], v33 offset0:74 offset1:107
	ds_read2_b32 v[70:71], v33 offset0:140 offset1:173
	ds_read2_b32 v[72:73], v33 offset0:206 offset1:239
	s_waitcnt lgkmcnt(7)
	v_cvt_pk_bf16_f32 v38, v56, v57
	s_lshl_b32 s28, s13, 1
	s_mov_b32 s29, s12
	s_waitcnt lgkmcnt(6)
	v_cvt_pk_bf16_f32 v39, v60, v61
	v_add_u32_e32 v46, s44, v31
	v_lshl_add_u64 v[44:45], v[8:9], 0, s[28:29]
	s_movk_i32 s4, 0x600
	s_waitcnt lgkmcnt(5)
	v_cvt_pk_bf16_f32 v40, v62, v63
	s_waitcnt lgkmcnt(4)
	v_cvt_pk_bf16_f32 v41, v64, v65
	v_mad_i64_i32 v[46:47], s[28:29], v46, s4, v[44:45]
	global_store_dwordx4 v[46:47], v[38:41], off
	s_nop 1
	v_add_u32_e32 v46, s44, v35
	v_mad_i64_i32 v[46:47], s[28:29], v46, s4, v[44:45]
	s_waitcnt lgkmcnt(3)
	v_cvt_pk_bf16_f32 v38, v66, v67
	s_waitcnt lgkmcnt(2)
	v_cvt_pk_bf16_f32 v39, v68, v69
	s_waitcnt lgkmcnt(1)
	v_cvt_pk_bf16_f32 v40, v70, v71
	s_waitcnt lgkmcnt(0)
	v_cvt_pk_bf16_f32 v41, v72, v73
	ds_read2_b32 v[56:57], v33 offset0:16 offset1:49
	ds_read2_b32 v[60:61], v33 offset0:82 offset1:115
	ds_read2_b32 v[62:63], v33 offset0:148 offset1:181
	ds_read2_b32 v[64:65], v33 offset0:214 offset1:247
	ds_read2_b32 v[66:67], v33 offset0:24 offset1:57
	ds_read2_b32 v[68:69], v33 offset0:90 offset1:123
	ds_read2_b32 v[70:71], v33 offset0:156 offset1:189
	ds_read2_b32 v[72:73], v33 offset0:222 offset1:255
	global_store_dwordx4 v[46:47], v[38:41], off
	s_nop 1
	v_add_u32_e32 v46, s44, v36
	v_mad_i64_i32 v[46:47], s[28:29], v46, s4, v[44:45]
	s_waitcnt lgkmcnt(7)
	v_cvt_pk_bf16_f32 v38, v56, v57
	s_waitcnt lgkmcnt(6)
	v_cvt_pk_bf16_f32 v39, v60, v61
	s_waitcnt lgkmcnt(5)
	v_cvt_pk_bf16_f32 v40, v62, v63
	s_waitcnt lgkmcnt(4)
	v_cvt_pk_bf16_f32 v41, v64, v65
	global_store_dwordx4 v[46:47], v[38:41], off
	s_nop 1
	v_add_u32_e32 v46, s44, v37
	s_mov_b32 s13, s7
	s_waitcnt lgkmcnt(3)
	v_cvt_pk_bf16_f32 v38, v66, v67
	s_waitcnt lgkmcnt(2)
	v_cvt_pk_bf16_f32 v39, v68, v69
	s_waitcnt lgkmcnt(1)
	v_cvt_pk_bf16_f32 v40, v70, v71
	s_waitcnt lgkmcnt(0)
	v_cvt_pk_bf16_f32 v41, v72, v73
	v_mad_i64_i32 v[42:43], s[28:29], v46, s4, v[44:45]
	global_store_dwordx4 v[42:43], v[38:41], off
	s_nop 1
	s_waitcnt lgkmcnt(0)
	s_andn2_b64 vcc, exec, s[40:41]
	s_cbranch_vccnz .LBB0_911

; #define LAS __attribute__((address_space(3)))
; __device__ __forceinline__ void tr_item(const float* __restrict__ W, int K, int N, bf16_t* __restrict__ WT, int dst_row0, int src_col0, int k0, LAS float* scr, int lane) {
;     if (src_col0 >= 0) {
;         const float* wp = W + (size_t)(k0 + (lane >> 5)) * N + src_col0 + (lane & 31);
;         float t[32];
; #pragma unroll
;         for (int i = 0; i < 32; ++i) t[i] = __builtin_nontemporal_load(wp + (size_t)(2 * i) * N);
.LBB0_896:
	s_lshr_b32 s18, s13, 1
	s_and_b32 s18, s18, 0x1c0
	v_add_u32_e32 v38, s18, v0
	s_lshl_b32 s7, s13, 5
	v_ashrrev_i32_e32 v39, 31, v38
	s_and_b32 s7, s7, 0xfe0
	v_lshlrev_b64 v[38:39], 14, v[38:39]
	v_lshl_add_u64 v[38:39], s[8:9], 0, v[38:39]
	s_lshl_b32 s28, s7, 2
	s_mov_b32 s29, s12
	v_lshl_add_u64 v[38:39], v[38:39], 0, s[28:29]
	v_lshlrev_b32_e32 v144, 2, v2
	v_lshl_add_u64 v[38:39], v[38:39], 0, v[144:145]
	s_mov_b32 s4, 0x8000
	v_add_co_u32_e32 v40, vcc, s4, v38
	s_mov_b32 s4, 0x18000
	s_nop 0
	v_addc_co_u32_e32 v41, vcc, 0, v39, vcc
	v_add_co_u32_e32 v42, vcc, s52, v38
	s_mov_b32 s24, 0x80000
	s_nop 0
	v_addc_co_u32_e32 v43, vcc, 0, v39, vcc
	v_add_co_u32_e32 v44, vcc, s4, v38
	s_mov_b32 s4, 0x20000
	s_nop 0
	v_addc_co_u32_e32 v45, vcc, 0, v39, vcc
	v_add_co_u32_e32 v46, vcc, s4, v38
	s_mov_b32 s4, 0x28000
	s_nop 0
	v_addc_co_u32_e32 v47, vcc, 0, v39, vcc
	s_waitcnt vmcnt(0)
	v_add_co_u32_e32 v48, vcc, s4, v38
	s_mov_b32 s4, 0x30000
	s_nop 0
	v_addc_co_u32_e32 v49, vcc, 0, v39, vcc
	v_add_co_u32_e32 v50, vcc, s4, v38
	s_mov_b32 s4, 0x38000
	s_nop 0
	v_addc_co_u32_e32 v51, vcc, 0, v39, vcc
	v_add_co_u32_e32 v52, vcc, s4, v38
	s_mov_b32 s4, 0x40000
	s_nop 0
	v_addc_co_u32_e32 v53, vcc, 0, v39, vcc
	global_load_dword v56, v[38:39], off nt
	global_load_dword v57, v[40:41], off nt
	global_load_dword v59, v[42:43], off nt
	global_load_dword v60, v[44:45], off nt
	global_load_dword v61, v[46:47], off nt
	global_load_dword v62, v[48:49], off nt
	global_load_dword v63, v[50:51], off nt
	global_load_dword v64, v[52:53], off nt
	v_add_co_u32_e32 v40, vcc, s4, v38
	s_mov_b32 s4, 0x48000
	s_nop 0
	v_addc_co_u32_e32 v41, vcc, 0, v39, vcc
	v_add_co_u32_e32 v42, vcc, s4, v38
	s_mov_b32 s4, 0x50000
	s_nop 0
	v_addc_co_u32_e32 v43, vcc, 0, v39, vcc
	v_add_co_u32_e32 v44, vcc, s4, v38
	s_mov_b32 s4, 0x58000
	s_nop 0
	v_addc_co_u32_e32 v45, vcc, 0, v39, vcc
	v_add_co_u32_e32 v46, vcc, s4, v38
	s_mov_b32 s4, 0x60000
	s_nop 0
	v_addc_co_u32_e32 v47, vcc, 0, v39, vcc
	v_add_co_u32_e32 v48, vcc, s4, v38
	s_mov_b32 s4, 0x68000
	s_nop 0
	v_addc_co_u32_e32 v49, vcc, 0, v39, vcc
	v_add_co_u32_e32 v50, vcc, s4, v38
	s_mov_b32 s4, 0x70000
	s_nop 0
	v_addc_co_u32_e32 v51, vcc, 0, v39, vcc
	v_add_co_u32_e32 v52, vcc, s4, v38
	s_mov_b32 s4, 0x78000
	s_nop 0
	v_addc_co_u32_e32 v53, vcc, 0, v39, vcc
	v_add_co_u32_e32 v54, vcc, s4, v38
	s_mov_b32 s4, 0xf8000
	s_nop 0
	v_addc_co_u32_e32 v55, vcc, 0, v39, vcc
	global_load_dword v65, v[40:41], off nt
	global_load_dword v66, v[42:43], off nt
	global_load_dword v67, v[44:45], off nt
	global_load_dword v68, v[46:47], off nt
	global_load_dword v69, v[48:49], off nt
	global_load_dword v70, v[50:51], off nt
	global_load_dword v71, v[52:53], off nt
	global_load_dword v72, v[54:55], off nt
	v_add_co_u32_e32 v40, vcc, s24, v38
	s_mov_b32 s24, 0x88000
	s_nop 0
	v_addc_co_u32_e32 v41, vcc, 0, v39, vcc
	v_add_co_u32_e32 v42, vcc, s24, v38
	s_mov_b32 s24, 0x90000
	s_nop 0
	v_addc_co_u32_e32 v43, vcc, 0, v39, vcc
	v_add_co_u32_e32 v44, vcc, s24, v38
	s_mov_b32 s24, 0x98000
	s_nop 0
	v_addc_co_u32_e32 v45, vcc, 0, v39, vcc
	v_add_co_u32_e32 v46, vcc, s24, v38
	s_mov_b32 s24, 0xa0000
	s_nop 0
	v_addc_co_u32_e32 v47, vcc, 0, v39, vcc
	v_add_co_u32_e32 v48, vcc, s24, v38
	s_mov_b32 s24, 0xa8000
	s_nop 0
	v_addc_co_u32_e32 v49, vcc, 0, v39, vcc
	v_add_co_u32_e32 v50, vcc, s24, v38
	s_mov_b32 s24, 0xb0000
	s_nop 0
	v_addc_co_u32_e32 v51, vcc, 0, v39, vcc
	v_add_co_u32_e32 v52, vcc, s24, v38
	s_mov_b32 s24, 0xb8000
	s_nop 0
	v_addc_co_u32_e32 v53, vcc, 0, v39, vcc
	v_add_co_u32_e32 v54, vcc, s24, v38
	s_mov_b32 s24, 0xc0000
	s_nop 0
	v_addc_co_u32_e32 v55, vcc, 0, v39, vcc
	global_load_dword v73, v[40:41], off nt
	global_load_dword v74, v[42:43], off nt
	global_load_dword v75, v[44:45], off nt
	global_load_dword v76, v[46:47], off nt
	global_load_dword v77, v[48:49], off nt
	global_load_dword v78, v[50:51], off nt
	global_load_dword v79, v[52:53], off nt
	s_nop 0
	global_load_dword v54, v[54:55], off nt
	v_add_co_u32_e32 v40, vcc, s24, v38
	s_mov_b32 s24, 0xc8000
	s_nop 0
	v_addc_co_u32_e32 v41, vcc, 0, v39, vcc
	v_add_co_u32_e32 v42, vcc, s24, v38
	s_mov_b32 s24, 0xd0000
	s_nop 0
	v_addc_co_u32_e32 v43, vcc, 0, v39, vcc
	v_add_co_u32_e32 v44, vcc, s24, v38
	s_mov_b32 s24, 0xd8000
	s_nop 0
	v_addc_co_u32_e32 v45, vcc, 0, v39, vcc
	v_add_co_u32_e32 v46, vcc, s24, v38
	s_mov_b32 s24, 0xe0000
	s_nop 0
	v_addc_co_u32_e32 v47, vcc, 0, v39, vcc
	v_add_co_u32_e32 v48, vcc, s24, v38
	s_mov_b32 s24, 0xe8000
	s_nop 0
	v_addc_co_u32_e32 v49, vcc, 0, v39, vcc
	v_add_co_u32_e32 v50, vcc, s24, v38
	s_mov_b32 s24, 0xf0000
	s_nop 0
	v_addc_co_u32_e32 v51, vcc, 0, v39, vcc
	v_add_co_u32_e32 v52, vcc, s24, v38
	s_lshl_b32 s28, s18, 1
	s_nop 0
	v_addc_co_u32_e32 v53, vcc, 0, v39, vcc
	v_add_co_u32_e32 v38, vcc, s4, v38
	s_nop 1
	v_addc_co_u32_e32 v39, vcc, 0, v39, vcc
	global_load_dword v40, v[40:41], off nt
	s_nop 0
	global_load_dword v41, v[42:43], off nt
	s_nop 0
	global_load_dword v42, v[44:45], off nt
	global_load_dword v43, v[46:47], off nt
	s_nop 0
	global_load_dword v44, v[48:49], off nt
	global_load_dword v45, v[50:51], off nt
	global_load_dword v46, v[52:53], off nt
	s_nop 0
	global_load_dword v38, v[38:39], off nt
	v_add_u32_e32 v39, 0x400, v6
	s_waitcnt vmcnt(0)
; #define LAS __attribute__((address_space(3)))
; __device__ __forceinline__ unsigned cvt_pk_bf16(float lo, float hi) { unsigned r; asm volatile("v_cvt_pk_bf16_f32 %0, %1, %2" : "=v"(r) : "v"(lo), "v"(hi)); return r; }
; #define LDS_WAIT() asm volatile("s_waitcnt lgkmcnt(0)" ::: "memory")
; __device__ __forceinline__ void tr_item(const float* __restrict__ W, int K, int N, bf16_t* __restrict__ WT, int dst_row0, int src_col0, int k0, LAS float* scr, int lane) {
;     ...
;         for (int i = 0; i < 32; ++i) scr[(2 * i + (lane >> 5)) * 33 + (lane & 31)] = t[i];
;     } else {
; #pragma unroll 8
;         for (int i = 0; i < 32; ++i) { const int kk = 2 * i + (lane >> 5); scr[kk * 33 + (lane & 31)] = 0.f; }
;     }
;     LDS_WAIT(); asm volatile("" ::: "memory");
;     const int c = lane & 7;
; #pragma unroll
;     for (int j = 0; j < 4; ++j) { const int n = (lane >> 3) + 8 * j; const LAS float* s = scr + (8 * c) * 33 + n;
;         u32x4 o; o.x = cvt_pk_bf16(s[0 * 33], s[1 * 33]); o.y = cvt_pk_bf16(s[2 * 33], s[3 * 33]); o.z = cvt_pk_bf16(s[4 * 33], s[5 * 33]); o.w = cvt_pk_bf16(s[6 * 33], s[7 * 33]);
;         *(u32x4*)(WT + (size_t)(dst_row0 + n) * K + k0 + 8 * c) = o; }
;     LDS_WAIT(); asm volatile("" ::: "memory");
	ds_write2_b32 v6, v56, v57 offset1:66
	ds_write2_b32 v6, v59, v60 offset0:132 offset1:198
	ds_write2_b32 v39, v61, v62 offset0:8 offset1:74
	ds_write2_b32 v39, v63, v64 offset0:140 offset1:206
	v_add_u32_e32 v39, 0x800, v6
	ds_write2_b32 v39, v65, v66 offset0:16 offset1:82
	ds_write2_b32 v39, v67, v68 offset0:148 offset1:214
	v_add_u32_e32 v39, 0xc00, v6
	ds_write2_b32 v39, v69, v70 offset0:24 offset1:90
	ds_write2_b32 v39, v71, v72 offset0:156 offset1:222
	v_add_u32_e32 v39, 0x1000, v6
	ds_write2_b32 v39, v73, v74 offset0:32 offset1:98
	ds_write2_b32 v39, v75, v76 offset0:164 offset1:230
	v_add_u32_e32 v39, 0x1400, v6
	ds_write2_b32 v39, v77, v78 offset0:40 offset1:106
	ds_write2_b32 v39, v79, v54 offset0:172 offset1:238
	v_add_u32_e32 v39, 0x1800, v6
	ds_write2_b32 v39, v40, v41 offset0:48 offset1:114
	ds_write2_b32 v39, v42, v43 offset0:180 offset1:246
	v_add_u32_e32 v39, 0x1c00, v6
	ds_write2_b32 v39, v44, v45 offset0:56 offset1:122
	ds_write2_b32 v39, v46, v38 offset0:188 offset1:254
	s_waitcnt lgkmcnt(0)
	ds_read2_b32 v[56:57], v33 offset1:33
	ds_read2_b32 v[60:61], v33 offset0:66 offset1:99
	ds_read2_b32 v[62:63], v33 offset0:132 offset1:165
	ds_read2_b32 v[64:65], v33 offset0:198 offset1:231
	ds_read2_b32 v[66:67], v33 offset0:8 offset1:41
	ds_read2_b32 v[68:69], v33 offset0:74 offset1:107
	ds_read2_b32 v[70:71], v33 offset0:140 offset1:173
	ds_read2_b32 v[72:73], v33 offset0:206 offset1:239
	s_waitcnt lgkmcnt(7)
	v_cvt_pk_bf16_f32 v38, v56, v57
	s_waitcnt lgkmcnt(6)
	v_cvt_pk_bf16_f32 v39, v60, v61
	s_waitcnt lgkmcnt(5)
	v_cvt_pk_bf16_f32 v40, v62, v63
	s_waitcnt lgkmcnt(4)
	v_cvt_pk_bf16_f32 v41, v64, v65
	v_add_u32_e32 v42, s7, v31
	v_ashrrev_i32_e32 v43, 31, v42
	v_lshl_add_u64 v[44:45], v[12:13], 0, s[28:29]
	v_lshlrev_b64 v[42:43], 10, v[42:43]
	v_lshl_add_u64 v[42:43], v[44:45], 0, v[42:43]
	global_store_dwordx4 v[42:43], v[38:41], off
	s_nop 1
	s_waitcnt lgkmcnt(3)
	s_nop 0
	v_cvt_pk_bf16_f32 v38, v66, v67
	s_waitcnt lgkmcnt(2)
	v_cvt_pk_bf16_f32 v39, v68, v69
	s_waitcnt lgkmcnt(1)
	v_cvt_pk_bf16_f32 v40, v70, v71
	s_waitcnt lgkmcnt(0)
	v_cvt_pk_bf16_f32 v41, v72, v73
	v_add_u32_e32 v42, s7, v35
	v_ashrrev_i32_e32 v43, 31, v42
	v_lshlrev_b64 v[42:43], 10, v[42:43]
	v_lshl_add_u64 v[42:43], v[44:45], 0, v[42:43]
	ds_read2_b32 v[56:57], v33 offset0:16 offset1:49
	ds_read2_b32 v[60:61], v33 offset0:82 offset1:115
	ds_read2_b32 v[62:63], v33 offset0:148 offset1:181
	ds_read2_b32 v[64:65], v33 offset0:214 offset1:247
	ds_read2_b32 v[66:67], v33 offset0:24 offset1:57
	ds_read2_b32 v[68:69], v33 offset0:90 offset1:123
	ds_read2_b32 v[70:71], v33 offset0:156 offset1:189
	ds_read2_b32 v[72:73], v33 offset0:222 offset1:255
	global_store_dwordx4 v[42:43], v[38:41], off
	s_nop 1
	s_waitcnt lgkmcnt(7)
	s_nop 0
	v_cvt_pk_bf16_f32 v38, v56, v57
	s_waitcnt lgkmcnt(6)
	v_cvt_pk_bf16_f32 v39, v60, v61
	s_waitcnt lgkmcnt(5)
	v_cvt_pk_bf16_f32 v40, v62, v63
	s_waitcnt lgkmcnt(4)
	v_cvt_pk_bf16_f32 v41, v64, v65
	v_add_u32_e32 v42, s7, v36
	v_ashrrev_i32_e32 v43, 31, v42
	v_lshlrev_b64 v[42:43], 10, v[42:43]
	v_lshl_add_u64 v[42:43], v[44:45], 0, v[42:43]
	global_store_dwordx4 v[42:43], v[38:41], off
	s_nop 1
	s_waitcnt lgkmcnt(3)
	s_nop 0
	v_cvt_pk_bf16_f32 v38, v66, v67
	s_waitcnt lgkmcnt(2)
	v_cvt_pk_bf16_f32 v39, v68, v69
	s_waitcnt lgkmcnt(1)
	v_cvt_pk_bf16_f32 v40, v70, v71
	s_waitcnt lgkmcnt(0)
	v_cvt_pk_bf16_f32 v41, v72, v73
	v_add_u32_e32 v42, s7, v37
	v_ashrrev_i32_e32 v43, 31, v42
	v_lshlrev_b64 v[42:43], 10, v[42:43]
	v_lshl_add_u64 v[42:43], v[44:45], 0, v[42:43]
	global_store_dwordx4 v[42:43], v[38:41], off
	s_nop 1
	s_waitcnt lgkmcnt(0)
	s_mov_b32 s7, s13
	s_andn2_b64 vcc, exec, s[40:41]
	s_cbranch_vccnz .LBB0_911

; #define LAS __attribute__((address_space(3)))
; __device__ __forceinline__ void tr_item(const float* __restrict__ W, int K, int N, bf16_t* __restrict__ WT, int dst_row0, int src_col0, int k0, LAS float* scr, int lane) {
;     if (src_col0 >= 0) {
;         const float* wp = W + (size_t)(k0 + (lane >> 5)) * N + src_col0 + (lane & 31);
;         float t[32];
; #pragma unroll
;         for (int i = 0; i < 32; ++i) t[i] = __builtin_nontemporal_load(wp + (size_t)(2 * i) * N);
.LBB0_901:
	s_and_b32 s18, s7, 0x3c0
	v_add_u32_e32 v38, s18, v0
	s_lshl_b32 s13, s7, 5
	v_ashrrev_i32_e32 v39, 31, v38
	s_and_b32 s13, s13, 0x7e0
	v_lshlrev_b64 v[38:39], 13, v[38:39]
	v_lshl_add_u64 v[38:39], s[14:15], 0, v[38:39]
	s_lshl_b32 s28, s13, 2
	s_mov_b32 s29, s12
	v_lshl_add_u64 v[38:39], v[38:39], 0, s[28:29]
	v_lshlrev_b32_e32 v144, 2, v2
	v_lshl_add_u64 v[38:39], v[38:39], 0, v[144:145]
	s_movk_i32 s4, 0x4000
	v_add_co_u32_e32 v40, vcc, s4, v38
	s_mov_b32 s4, 0x8000
	s_nop 0
	v_addc_co_u32_e32 v41, vcc, 0, v39, vcc
	v_add_co_u32_e32 v42, vcc, s4, v38
	s_mov_b32 s4, 0xc000
	s_nop 0
	v_addc_co_u32_e32 v43, vcc, 0, v39, vcc
	v_add_co_u32_e32 v44, vcc, s4, v38
	s_mov_b32 s4, 0x14000
	s_nop 0
	v_addc_co_u32_e32 v45, vcc, 0, v39, vcc
	v_add_co_u32_e32 v46, vcc, s52, v38
	s_lshl_b32 s28, s18, 1
	s_nop 0
	v_addc_co_u32_e32 v47, vcc, 0, v39, vcc
	s_waitcnt vmcnt(0)
	v_add_co_u32_e32 v48, vcc, s4, v38
	s_mov_b32 s4, 0x18000
	s_nop 0
	v_addc_co_u32_e32 v49, vcc, 0, v39, vcc
	v_add_co_u32_e32 v50, vcc, s4, v38
	s_mov_b32 s4, 0x1c000
	s_nop 0
	v_addc_co_u32_e32 v51, vcc, 0, v39, vcc
	v_add_co_u32_e32 v52, vcc, s4, v38
	s_mov_b32 s4, 0x20000
	s_nop 0
	v_addc_co_u32_e32 v53, vcc, 0, v39, vcc
	global_load_dword v56, v[38:39], off nt
	global_load_dword v57, v[40:41], off nt
	global_load_dword v59, v[42:43], off nt
	global_load_dword v60, v[44:45], off nt
	global_load_dword v61, v[46:47], off nt
	global_load_dword v62, v[48:49], off nt
	global_load_dword v63, v[50:51], off nt
	global_load_dword v64, v[52:53], off nt
	v_add_co_u32_e32 v40, vcc, s4, v38
	s_mov_b32 s4, 0x24000
	s_nop 0
	v_addc_co_u32_e32 v41, vcc, 0, v39, vcc
	v_add_co_u32_e32 v42, vcc, s4, v38
	s_mov_b32 s4, 0x28000
	s_nop 0
	v_addc_co_u32_e32 v43, vcc, 0, v39, vcc
	v_add_co_u32_e32 v44, vcc, s4, v38
	s_mov_b32 s4, 0x2c000
	s_nop 0
	v_addc_co_u32_e32 v45, vcc, 0, v39, vcc
	v_add_co_u32_e32 v46, vcc, s4, v38
	s_mov_b32 s4, 0x30000
	s_nop 0
	v_addc_co_u32_e32 v47, vcc, 0, v39, vcc
	v_add_co_u32_e32 v48, vcc, s4, v38
	s_mov_b32 s4, 0x34000
	s_nop 0
	v_addc_co_u32_e32 v49, vcc, 0, v39, vcc
	v_add_co_u32_e32 v50, vcc, s4, v38
	s_mov_b32 s4, 0x38000
	s_nop 0
	v_addc_co_u32_e32 v51, vcc, 0, v39, vcc
	v_add_co_u32_e32 v52, vcc, s4, v38
	s_mov_b32 s4, 0x3c000
	s_nop 0
	v_addc_co_u32_e32 v53, vcc, 0, v39, vcc
	v_add_co_u32_e32 v54, vcc, s4, v38
	s_mov_b32 s4, 0x40000
	s_nop 0
	v_addc_co_u32_e32 v55, vcc, 0, v39, vcc
	global_load_dword v65, v[40:41], off nt
	global_load_dword v66, v[42:43], off nt
	global_load_dword v67, v[44:45], off nt
	global_load_dword v68, v[46:47], off nt
	global_load_dword v69, v[48:49], off nt
	global_load_dword v70, v[50:51], off nt
	global_load_dword v71, v[52:53], off nt
	global_load_dword v72, v[54:55], off nt
	v_add_co_u32_e32 v40, vcc, s4, v38
	s_mov_b32 s4, 0x44000
	s_nop 0
	v_addc_co_u32_e32 v41, vcc, 0, v39, vcc
	v_add_co_u32_e32 v42, vcc, s4, v38
	s_mov_b32 s4, 0x48000
	s_nop 0
	v_addc_co_u32_e32 v43, vcc, 0, v39, vcc
	v_add_co_u32_e32 v44, vcc, s4, v38
	s_mov_b32 s4, 0x4c000
	s_nop 0
	v_addc_co_u32_e32 v45, vcc, 0, v39, vcc
	v_add_co_u32_e32 v46, vcc, s4, v38
	s_mov_b32 s4, 0x50000
	s_nop 0
	v_addc_co_u32_e32 v47, vcc, 0, v39, vcc
	v_add_co_u32_e32 v48, vcc, s4, v38
	s_mov_b32 s4, 0x54000
	s_nop 0
	v_addc_co_u32_e32 v49, vcc, 0, v39, vcc
	v_add_co_u32_e32 v50, vcc, s4, v38
	s_mov_b32 s4, 0x58000
	s_nop 0
	v_addc_co_u32_e32 v51, vcc, 0, v39, vcc
	v_add_co_u32_e32 v52, vcc, s4, v38
	s_mov_b32 s4, 0x5c000
	s_nop 0
	v_addc_co_u32_e32 v53, vcc, 0, v39, vcc
	v_add_co_u32_e32 v54, vcc, s4, v38
	s_mov_b32 s4, 0x60000
	s_nop 0
	v_addc_co_u32_e32 v55, vcc, 0, v39, vcc
	global_load_dword v73, v[40:41], off nt
	global_load_dword v74, v[42:43], off nt
	global_load_dword v75, v[44:45], off nt
	global_load_dword v76, v[46:47], off nt
	global_load_dword v77, v[48:49], off nt
	global_load_dword v78, v[50:51], off nt
	global_load_dword v79, v[52:53], off nt
	s_nop 0
	global_load_dword v54, v[54:55], off nt
	v_add_co_u32_e32 v40, vcc, s4, v38
	s_mov_b32 s4, 0x64000
	s_nop 0
	v_addc_co_u32_e32 v41, vcc, 0, v39, vcc
	v_add_co_u32_e32 v42, vcc, s4, v38
	s_mov_b32 s4, 0x68000
	s_nop 0
	v_addc_co_u32_e32 v43, vcc, 0, v39, vcc
	v_add_co_u32_e32 v44, vcc, s4, v38
	s_mov_b32 s4, 0x6c000
	s_nop 0
	v_addc_co_u32_e32 v45, vcc, 0, v39, vcc
	v_add_co_u32_e32 v46, vcc, s4, v38
	s_mov_b32 s4, 0x70000
	s_nop 0
	v_addc_co_u32_e32 v47, vcc, 0, v39, vcc
	v_add_co_u32_e32 v48, vcc, s4, v38
	s_mov_b32 s4, 0x74000
	s_nop 0
	v_addc_co_u32_e32 v49, vcc, 0, v39, vcc
	v_add_co_u32_e32 v50, vcc, s4, v38
	s_mov_b32 s4, 0x78000
	s_nop 0
	v_addc_co_u32_e32 v51, vcc, 0, v39, vcc
	v_add_co_u32_e32 v52, vcc, s4, v38
	s_mov_b32 s4, 0x7c000
	s_nop 0
	v_addc_co_u32_e32 v53, vcc, 0, v39, vcc
	v_add_co_u32_e32 v38, vcc, s4, v38
	s_nop 1
	v_addc_co_u32_e32 v39, vcc, 0, v39, vcc
	global_load_dword v40, v[40:41], off nt
	s_nop 0
	global_load_dword v41, v[42:43], off nt
	s_nop 0
	global_load_dword v42, v[44:45], off nt
	global_load_dword v43, v[46:47], off nt
	s_nop 0
	global_load_dword v44, v[48:49], off nt
	global_load_dword v45, v[50:51], off nt
	global_load_dword v46, v[52:53], off nt
	s_nop 0
	global_load_dword v38, v[38:39], off nt
	v_add_u32_e32 v39, 0x400, v6
	s_waitcnt vmcnt(0)
; #define LAS __attribute__((address_space(3)))
; __device__ __forceinline__ unsigned cvt_pk_bf16(float lo, float hi) { unsigned r; asm volatile("v_cvt_pk_bf16_f32 %0, %1, %2" : "=v"(r) : "v"(lo), "v"(hi)); return r; }
; #define LDS_WAIT() asm volatile("s_waitcnt lgkmcnt(0)" ::: "memory")
; __device__ __forceinline__ void tr_item(const float* __restrict__ W, int K, int N, bf16_t* __restrict__ WT, int dst_row0, int src_col0, int k0, LAS float* scr, int lane) {
;     ...
;         for (int i = 0; i < 32; ++i) scr[(2 * i + (lane >> 5)) * 33 + (lane & 31)] = t[i];
;     } else {
; #pragma unroll 8
;         for (int i = 0; i < 32; ++i) { const int kk = 2 * i + (lane >> 5); scr[kk * 33 + (lane & 31)] = 0.f; }
;     }
;     LDS_WAIT(); asm volatile("" ::: "memory");
;     const int c = lane & 7;
; #pragma unroll
;     for (int j = 0; j < 4; ++j) { const int n = (lane >> 3) + 8 * j; const LAS float* s = scr + (8 * c) * 33 + n;
;         u32x4 o; o.x = cvt_pk_bf16(s[0 * 33], s[1 * 33]); o.y = cvt_pk_bf16(s[2 * 33], s[3 * 33]); o.z = cvt_pk_bf16(s[4 * 33], s[5 * 33]); o.w = cvt_pk_bf16(s[6 * 33], s[7 * 33]);
;         *(u32x4*)(WT + (size_t)(dst_row0 + n) * K + k0 + 8 * c) = o; }
;     LDS_WAIT(); asm volatile("" ::: "memory");
	ds_write2_b32 v6, v56, v57 offset1:66
	ds_write2_b32 v6, v59, v60 offset0:132 offset1:198
	ds_write2_b32 v39, v61, v62 offset0:8 offset1:74
	ds_write2_b32 v39, v63, v64 offset0:140 offset1:206
	v_add_u32_e32 v39, 0x800, v6
	ds_write2_b32 v39, v65, v66 offset0:16 offset1:82
	ds_write2_b32 v39, v67, v68 offset0:148 offset1:214
	v_add_u32_e32 v39, 0xc00, v6
	ds_write2_b32 v39, v69, v70 offset0:24 offset1:90
	ds_write2_b32 v39, v71, v72 offset0:156 offset1:222
	v_add_u32_e32 v39, 0x1000, v6
	ds_write2_b32 v39, v73, v74 offset0:32 offset1:98
	ds_write2_b32 v39, v75, v76 offset0:164 offset1:230
	v_add_u32_e32 v39, 0x1400, v6
	ds_write2_b32 v39, v77, v78 offset0:40 offset1:106
	ds_write2_b32 v39, v79, v54 offset0:172 offset1:238
	v_add_u32_e32 v39, 0x1800, v6
	ds_write2_b32 v39, v40, v41 offset0:48 offset1:114
	ds_write2_b32 v39, v42, v43 offset0:180 offset1:246
	v_add_u32_e32 v39, 0x1c00, v6
	ds_write2_b32 v39, v44, v45 offset0:56 offset1:122
	ds_write2_b32 v39, v46, v38 offset0:188 offset1:254
	s_waitcnt lgkmcnt(0)
	ds_read2_b32 v[56:57], v33 offset1:33
	ds_read2_b32 v[60:61], v33 offset0:66 offset1:99
	ds_read2_b32 v[62:63], v33 offset0:132 offset1:165
	ds_read2_b32 v[64:65], v33 offset0:198 offset1:231
	ds_read2_b32 v[66:67], v33 offset0:8 offset1:41
	ds_read2_b32 v[68:69], v33 offset0:74 offset1:107
	ds_read2_b32 v[70:71], v33 offset0:140 offset1:173
	ds_read2_b32 v[72:73], v33 offset0:206 offset1:239
	s_waitcnt lgkmcnt(7)
	v_cvt_pk_bf16_f32 v38, v56, v57
	s_waitcnt lgkmcnt(6)
	v_cvt_pk_bf16_f32 v39, v60, v61
	s_waitcnt lgkmcnt(5)
	v_cvt_pk_bf16_f32 v40, v62, v63
	s_waitcnt lgkmcnt(4)
	v_cvt_pk_bf16_f32 v41, v64, v65
	v_add_u32_e32 v42, s13, v31
	v_ashrrev_i32_e32 v43, 31, v42
	v_lshl_add_u64 v[44:45], v[14:15], 0, s[28:29]
	v_lshlrev_b64 v[42:43], 11, v[42:43]
	v_lshl_add_u64 v[42:43], v[44:45], 0, v[42:43]
	global_store_dwordx4 v[42:43], v[38:41], off
	s_nop 1
	s_waitcnt lgkmcnt(3)
	s_nop 0
	v_cvt_pk_bf16_f32 v38, v66, v67
	s_waitcnt lgkmcnt(2)
	v_cvt_pk_bf16_f32 v39, v68, v69
	s_waitcnt lgkmcnt(1)
	v_cvt_pk_bf16_f32 v40, v70, v71
	s_waitcnt lgkmcnt(0)
	v_cvt_pk_bf16_f32 v41, v72, v73
	v_add_u32_e32 v42, s13, v35
	v_ashrrev_i32_e32 v43, 31, v42
	v_lshlrev_b64 v[42:43], 11, v[42:43]
	v_lshl_add_u64 v[42:43], v[44:45], 0, v[42:43]
	ds_read2_b32 v[56:57], v33 offset0:16 offset1:49
	ds_read2_b32 v[60:61], v33 offset0:82 offset1:115
	ds_read2_b32 v[62:63], v33 offset0:148 offset1:181
	ds_read2_b32 v[64:65], v33 offset0:214 offset1:247
	ds_read2_b32 v[66:67], v33 offset0:24 offset1:57
	ds_read2_b32 v[68:69], v33 offset0:90 offset1:123
	ds_read2_b32 v[70:71], v33 offset0:156 offset1:189
	ds_read2_b32 v[72:73], v33 offset0:222 offset1:255
	global_store_dwordx4 v[42:43], v[38:41], off
	s_nop 1
	s_waitcnt lgkmcnt(7)
	s_nop 0
	v_cvt_pk_bf16_f32 v38, v56, v57
	s_waitcnt lgkmcnt(6)
	v_cvt_pk_bf16_f32 v39, v60, v61
	s_waitcnt lgkmcnt(5)
	v_cvt_pk_bf16_f32 v40, v62, v63
	s_waitcnt lgkmcnt(4)
	v_cvt_pk_bf16_f32 v41, v64, v65
	v_add_u32_e32 v42, s13, v36
	v_ashrrev_i32_e32 v43, 31, v42
	v_lshlrev_b64 v[42:43], 11, v[42:43]
	v_lshl_add_u64 v[42:43], v[44:45], 0, v[42:43]
	global_store_dwordx4 v[42:43], v[38:41], off
	s_nop 1
	s_waitcnt lgkmcnt(3)
	s_nop 0
	v_cvt_pk_bf16_f32 v38, v66, v67
	s_waitcnt lgkmcnt(2)
	v_cvt_pk_bf16_f32 v39, v68, v69
	s_waitcnt lgkmcnt(1)
	v_cvt_pk_bf16_f32 v40, v70, v71
	s_waitcnt lgkmcnt(0)
	v_cvt_pk_bf16_f32 v41, v72, v73
	v_add_u32_e32 v42, s13, v37
	v_ashrrev_i32_e32 v43, 31, v42
	v_lshlrev_b64 v[42:43], 11, v[42:43]
	v_lshl_add_u64 v[42:43], v[44:45], 0, v[42:43]
	global_store_dwordx4 v[42:43], v[38:41], off
	s_nop 1
	s_waitcnt lgkmcnt(0)
	s_mov_b32 s13, s7
	s_andn2_b64 vcc, exec, s[40:41]
	s_cbranch_vccnz .LBB0_911

; #define LAS __attribute__((address_space(3)))
; __device__ __forceinline__ void tr_item(const float* __restrict__ W, int K, int N, bf16_t* __restrict__ WT, int dst_row0, int src_col0, int k0, LAS float* scr, int lane) {
;     if (src_col0 >= 0) {
;         const float* wp = W + (size_t)(k0 + (lane >> 5)) * N + src_col0 + (lane & 31);
;         float t[32];
; #pragma unroll
;         for (int i = 0; i < 32; ++i) t[i] = __builtin_nontemporal_load(wp + (size_t)(2 * i) * N);
.LBB0_906:
	s_and_b32 s18, s13, 0x7c0
	v_add_u32_e32 v38, s18, v0
	s_lshl_b32 s7, s13, 5
	v_ashrrev_i32_e32 v39, 31, v38
	s_and_b32 s7, s7, 0x7e0
	v_lshlrev_b64 v[38:39], 13, v[38:39]
	v_lshl_add_u64 v[38:39], s[34:35], 0, v[38:39]
	s_lshl_b32 s28, s7, 2
	s_mov_b32 s29, s12
	v_lshl_add_u64 v[38:39], v[38:39], 0, s[28:29]
	v_lshlrev_b32_e32 v144, 2, v2
	v_lshl_add_u64 v[38:39], v[38:39], 0, v[144:145]
	s_movk_i32 s4, 0x4000
	v_add_co_u32_e32 v40, vcc, s4, v38
	s_mov_b32 s4, 0x8000
	s_nop 0
	v_addc_co_u32_e32 v41, vcc, 0, v39, vcc
	v_add_co_u32_e32 v42, vcc, s4, v38
	s_mov_b32 s4, 0xc000
	s_nop 0
	v_addc_co_u32_e32 v43, vcc, 0, v39, vcc
	v_add_co_u32_e32 v44, vcc, s4, v38
	s_mov_b32 s4, 0x14000
	s_nop 0
	v_addc_co_u32_e32 v45, vcc, 0, v39, vcc
	v_add_co_u32_e32 v46, vcc, s52, v38
	s_lshl_b32 s28, s18, 1
	s_nop 0
	v_addc_co_u32_e32 v47, vcc, 0, v39, vcc
	s_waitcnt vmcnt(0)
	v_add_co_u32_e32 v48, vcc, s4, v38
	s_mov_b32 s4, 0x18000
	s_nop 0
	v_addc_co_u32_e32 v49, vcc, 0, v39, vcc
	v_add_co_u32_e32 v50, vcc, s4, v38
	s_mov_b32 s4, 0x1c000
	s_nop 0
	v_addc_co_u32_e32 v51, vcc, 0, v39, vcc
	v_add_co_u32_e32 v52, vcc, s4, v38
	s_mov_b32 s4, 0x20000
	s_nop 0
	v_addc_co_u32_e32 v53, vcc, 0, v39, vcc
	global_load_dword v56, v[38:39], off nt
	global_load_dword v57, v[40:41], off nt
	global_load_dword v59, v[42:43], off nt
	global_load_dword v60, v[44:45], off nt
	global_load_dword v61, v[46:47], off nt
	global_load_dword v62, v[48:49], off nt
	global_load_dword v63, v[50:51], off nt
	global_load_dword v64, v[52:53], off nt
	v_add_co_u32_e32 v40, vcc, s4, v38
	s_mov_b32 s4, 0x24000
	s_nop 0
	v_addc_co_u32_e32 v41, vcc, 0, v39, vcc
	v_add_co_u32_e32 v42, vcc, s4, v38
	s_mov_b32 s4, 0x28000
	s_nop 0
	v_addc_co_u32_e32 v43, vcc, 0, v39, vcc
	v_add_co_u32_e32 v44, vcc, s4, v38
	s_mov_b32 s4, 0x2c000
	s_nop 0
	v_addc_co_u32_e32 v45, vcc, 0, v39, vcc
	v_add_co_u32_e32 v46, vcc, s4, v38
	s_mov_b32 s4, 0x30000
	s_nop 0
	v_addc_co_u32_e32 v47, vcc, 0, v39, vcc
	v_add_co_u32_e32 v48, vcc, s4, v38
	s_mov_b32 s4, 0x34000
	s_nop 0
	v_addc_co_u32_e32 v49, vcc, 0, v39, vcc
	v_add_co_u32_e32 v50, vcc, s4, v38
	s_mov_b32 s4, 0x38000
	s_nop 0
	v_addc_co_u32_e32 v51, vcc, 0, v39, vcc
	v_add_co_u32_e32 v52, vcc, s4, v38
	s_mov_b32 s4, 0x3c000
	s_nop 0
	v_addc_co_u32_e32 v53, vcc, 0, v39, vcc
	v_add_co_u32_e32 v54, vcc, s4, v38
	s_mov_b32 s4, 0x40000
	s_nop 0
	v_addc_co_u32_e32 v55, vcc, 0, v39, vcc
	global_load_dword v65, v[40:41], off nt
	global_load_dword v66, v[42:43], off nt
	global_load_dword v67, v[44:45], off nt
	global_load_dword v68, v[46:47], off nt
	global_load_dword v69, v[48:49], off nt
	global_load_dword v70, v[50:51], off nt
	global_load_dword v71, v[52:53], off nt
	global_load_dword v72, v[54:55], off nt
	v_add_co_u32_e32 v40, vcc, s4, v38
	s_mov_b32 s4, 0x44000
	s_nop 0
	v_addc_co_u32_e32 v41, vcc, 0, v39, vcc
	v_add_co_u32_e32 v42, vcc, s4, v38
	s_mov_b32 s4, 0x48000
	s_nop 0
	v_addc_co_u32_e32 v43, vcc, 0, v39, vcc
	v_add_co_u32_e32 v44, vcc, s4, v38
	s_mov_b32 s4, 0x4c000
	s_nop 0
	v_addc_co_u32_e32 v45, vcc, 0, v39, vcc
	v_add_co_u32_e32 v46, vcc, s4, v38
	s_mov_b32 s4, 0x50000
	s_nop 0
	v_addc_co_u32_e32 v47, vcc, 0, v39, vcc
	v_add_co_u32_e32 v48, vcc, s4, v38
	s_mov_b32 s4, 0x54000
	s_nop 0
	v_addc_co_u32_e32 v49, vcc, 0, v39, vcc
	v_add_co_u32_e32 v50, vcc, s4, v38
	s_mov_b32 s4, 0x58000
	s_nop 0
	v_addc_co_u32_e32 v51, vcc, 0, v39, vcc
	v_add_co_u32_e32 v52, vcc, s4, v38
	s_mov_b32 s4, 0x5c000
	s_nop 0
	v_addc_co_u32_e32 v53, vcc, 0, v39, vcc
	v_add_co_u32_e32 v54, vcc, s4, v38
	s_mov_b32 s4, 0x60000
	s_nop 0
	v_addc_co_u32_e32 v55, vcc, 0, v39, vcc
	global_load_dword v73, v[40:41], off nt
	global_load_dword v74, v[42:43], off nt
	global_load_dword v75, v[44:45], off nt
	global_load_dword v76, v[46:47], off nt
	global_load_dword v77, v[48:49], off nt
	global_load_dword v78, v[50:51], off nt
	global_load_dword v79, v[52:53], off nt
	s_nop 0
	global_load_dword v54, v[54:55], off nt
	v_add_co_u32_e32 v40, vcc, s4, v38
	s_mov_b32 s4, 0x64000
	s_nop 0
	v_addc_co_u32_e32 v41, vcc, 0, v39, vcc
	v_add_co_u32_e32 v42, vcc, s4, v38
	s_mov_b32 s4, 0x68000
	s_nop 0
	v_addc_co_u32_e32 v43, vcc, 0, v39, vcc
	v_add_co_u32_e32 v44, vcc, s4, v38
	s_mov_b32 s4, 0x6c000
	s_nop 0
	v_addc_co_u32_e32 v45, vcc, 0, v39, vcc
	v_add_co_u32_e32 v46, vcc, s4, v38
	s_mov_b32 s4, 0x70000
	s_nop 0
	v_addc_co_u32_e32 v47, vcc, 0, v39, vcc
	v_add_co_u32_e32 v48, vcc, s4, v38
	s_mov_b32 s4, 0x74000
	s_nop 0
	v_addc_co_u32_e32 v49, vcc, 0, v39, vcc
	v_add_co_u32_e32 v50, vcc, s4, v38
	s_mov_b32 s4, 0x78000
	s_nop 0
	v_addc_co_u32_e32 v51, vcc, 0, v39, vcc
	v_add_co_u32_e32 v52, vcc, s4, v38
	s_mov_b32 s4, 0x7c000
	s_nop 0
	v_addc_co_u32_e32 v53, vcc, 0, v39, vcc
	v_add_co_u32_e32 v38, vcc, s4, v38
	s_nop 1
	v_addc_co_u32_e32 v39, vcc, 0, v39, vcc
	global_load_dword v40, v[40:41], off nt
	s_nop 0
	global_load_dword v41, v[42:43], off nt
	s_nop 0
	global_load_dword v42, v[44:45], off nt
	global_load_dword v43, v[46:47], off nt
	s_nop 0
	global_load_dword v44, v[48:49], off nt
	global_load_dword v45, v[50:51], off nt
	global_load_dword v46, v[52:53], off nt
	s_nop 0
	global_load_dword v38, v[38:39], off nt
	v_add_u32_e32 v39, 0x400, v6
	s_waitcnt vmcnt(0)
; #define LAS __attribute__((address_space(3)))
; __device__ __forceinline__ unsigned cvt_pk_bf16(float lo, float hi) { unsigned r; asm volatile("v_cvt_pk_bf16_f32 %0, %1, %2" : "=v"(r) : "v"(lo), "v"(hi)); return r; }
; #define LDS_WAIT() asm volatile("s_waitcnt lgkmcnt(0)" ::: "memory")
; __device__ __forceinline__ void tr_item(const float* __restrict__ W, int K, int N, bf16_t* __restrict__ WT, int dst_row0, int src_col0, int k0, LAS float* scr, int lane) {
;     ...
;         for (int i = 0; i < 32; ++i) scr[(2 * i + (lane >> 5)) * 33 + (lane & 31)] = t[i];
;     } else {
; #pragma unroll 8
;         for (int i = 0; i < 32; ++i) { const int kk = 2 * i + (lane >> 5); scr[kk * 33 + (lane & 31)] = 0.f; }
;     }
;     LDS_WAIT(); asm volatile("" ::: "memory");
;     const int c = lane & 7;
; #pragma unroll
;     for (int j = 0; j < 4; ++j) { const int n = (lane >> 3) + 8 * j; const LAS float* s = scr + (8 * c) * 33 + n;
;         u32x4 o; o.x = cvt_pk_bf16(s[0 * 33], s[1 * 33]); o.y = cvt_pk_bf16(s[2 * 33], s[3 * 33]); o.z = cvt_pk_bf16(s[4 * 33], s[5 * 33]); o.w = cvt_pk_bf16(s[6 * 33], s[7 * 33]);
;         *(u32x4*)(WT + (size_t)(dst_row0 + n) * K + k0 + 8 * c) = o; }
;     LDS_WAIT(); asm volatile("" ::: "memory");
	ds_write2_b32 v6, v56, v57 offset1:66
	ds_write2_b32 v6, v59, v60 offset0:132 offset1:198
	ds_write2_b32 v39, v61, v62 offset0:8 offset1:74
	ds_write2_b32 v39, v63, v64 offset0:140 offset1:206
	v_add_u32_e32 v39, 0x800, v6
	ds_write2_b32 v39, v65, v66 offset0:16 offset1:82
	ds_write2_b32 v39, v67, v68 offset0:148 offset1:214
	v_add_u32_e32 v39, 0xc00, v6
	ds_write2_b32 v39, v69, v70 offset0:24 offset1:90
	ds_write2_b32 v39, v71, v72 offset0:156 offset1:222
	v_add_u32_e32 v39, 0x1000, v6
	ds_write2_b32 v39, v73, v74 offset0:32 offset1:98
	ds_write2_b32 v39, v75, v76 offset0:164 offset1:230
	v_add_u32_e32 v39, 0x1400, v6
	ds_write2_b32 v39, v77, v78 offset0:40 offset1:106
	ds_write2_b32 v39, v79, v54 offset0:172 offset1:238
	v_add_u32_e32 v39, 0x1800, v6
	ds_write2_b32 v39, v40, v41 offset0:48 offset1:114
	ds_write2_b32 v39, v42, v43 offset0:180 offset1:246
	v_add_u32_e32 v39, 0x1c00, v6
	ds_write2_b32 v39, v44, v45 offset0:56 offset1:122
	ds_write2_b32 v39, v46, v38 offset0:188 offset1:254
	s_waitcnt lgkmcnt(0)
	ds_read2_b32 v[56:57], v33 offset1:33
	ds_read2_b32 v[60:61], v33 offset0:66 offset1:99
	ds_read2_b32 v[62:63], v33 offset0:132 offset1:165
	ds_read2_b32 v[64:65], v33 offset0:198 offset1:231
	ds_read2_b32 v[66:67], v33 offset0:8 offset1:41
	ds_read2_b32 v[68:69], v33 offset0:74 offset1:107
	ds_read2_b32 v[70:71], v33 offset0:140 offset1:173
	ds_read2_b32 v[72:73], v33 offset0:206 offset1:239
	s_waitcnt lgkmcnt(7)
	v_cvt_pk_bf16_f32 v38, v56, v57
	s_waitcnt lgkmcnt(6)
	v_cvt_pk_bf16_f32 v39, v60, v61
	s_waitcnt lgkmcnt(5)
	v_cvt_pk_bf16_f32 v40, v62, v63
	s_waitcnt lgkmcnt(4)
	v_cvt_pk_bf16_f32 v41, v64, v65
	v_add_u32_e32 v42, s7, v31
	v_ashrrev_i32_e32 v43, 31, v42
	v_lshl_add_u64 v[44:45], v[16:17], 0, s[28:29]
	v_lshlrev_b64 v[42:43], 12, v[42:43]
	v_lshl_add_u64 v[42:43], v[44:45], 0, v[42:43]
	global_store_dwordx4 v[42:43], v[38:41], off
	s_nop 1
	s_waitcnt lgkmcnt(3)
	s_nop 0
	v_cvt_pk_bf16_f32 v38, v66, v67
	s_waitcnt lgkmcnt(2)
	v_cvt_pk_bf16_f32 v39, v68, v69
	s_waitcnt lgkmcnt(1)
	v_cvt_pk_bf16_f32 v40, v70, v71
	s_waitcnt lgkmcnt(0)
	v_cvt_pk_bf16_f32 v41, v72, v73
	v_add_u32_e32 v42, s7, v35
	v_ashrrev_i32_e32 v43, 31, v42
	v_lshlrev_b64 v[42:43], 12, v[42:43]
	v_lshl_add_u64 v[42:43], v[44:45], 0, v[42:43]
	ds_read2_b32 v[56:57], v33 offset0:16 offset1:49
	ds_read2_b32 v[60:61], v33 offset0:82 offset1:115
	ds_read2_b32 v[62:63], v33 offset0:148 offset1:181
	ds_read2_b32 v[64:65], v33 offset0:214 offset1:247
	ds_read2_b32 v[66:67], v33 offset0:24 offset1:57
	ds_read2_b32 v[68:69], v33 offset0:90 offset1:123
	ds_read2_b32 v[70:71], v33 offset0:156 offset1:189
	ds_read2_b32 v[72:73], v33 offset0:222 offset1:255
	global_store_dwordx4 v[42:43], v[38:41], off
	s_nop 1
	s_waitcnt lgkmcnt(7)
	s_nop 0
	v_cvt_pk_bf16_f32 v38, v56, v57
	s_waitcnt lgkmcnt(6)
	v_cvt_pk_bf16_f32 v39, v60, v61
	s_waitcnt lgkmcnt(5)
	v_cvt_pk_bf16_f32 v40, v62, v63
	s_waitcnt lgkmcnt(4)
	v_cvt_pk_bf16_f32 v41, v64, v65
	v_add_u32_e32 v42, s7, v36
	v_ashrrev_i32_e32 v43, 31, v42
	v_lshlrev_b64 v[42:43], 12, v[42:43]
	v_lshl_add_u64 v[42:43], v[44:45], 0, v[42:43]
	global_store_dwordx4 v[42:43], v[38:41], off
	s_nop 1
	s_waitcnt lgkmcnt(3)
	s_nop 0
	v_cvt_pk_bf16_f32 v38, v66, v67
	s_waitcnt lgkmcnt(2)
	v_cvt_pk_bf16_f32 v39, v68, v69
	s_waitcnt lgkmcnt(1)
	v_cvt_pk_bf16_f32 v40, v70, v71
	s_waitcnt lgkmcnt(0)
	v_cvt_pk_bf16_f32 v41, v72, v73
	v_add_u32_e32 v42, s7, v37
	v_ashrrev_i32_e32 v43, 31, v42
	v_lshlrev_b64 v[42:43], 12, v[42:43]
	v_lshl_add_u64 v[42:43], v[44:45], 0, v[42:43]
	global_store_dwordx4 v[42:43], v[38:41], off
	s_nop 1
	s_waitcnt lgkmcnt(0)
	s_mov_b32 s7, s13
	s_andn2_b64 vcc, exec, s[40:41]
	s_cbranch_vccnz .LBB0_911

; #define LAS __attribute__((address_space(3)))
; __device__ __forceinline__ void tr_item(const float* __restrict__ W, int K, int N, bf16_t* __restrict__ WT, int dst_row0, int src_col0, int k0, LAS float* scr, int lane) {
;     if (src_col0 >= 0) {
;         const float* wp = W + (size_t)(k0 + (lane >> 5)) * N + src_col0 + (lane & 31);
;         float t[32];
; #pragma unroll
;         for (int i = 0; i < 32; ++i) t[i] = __builtin_nontemporal_load(wp + (size_t)(2 * i) * N);
.LBB0_910:
	s_and_b32 s7, s13, 0xffc0
	v_add_u32_e32 v38, s7, v0
	v_ashrrev_i32_e32 v39, 31, v38
	s_lshl_b32 s13, s13, 5
	v_lshlrev_b64 v[38:39], 13, v[38:39]
	s_and_b32 s40, s13, 0x7fe007e0
	v_lshl_add_u64 v[38:39], s[38:39], 0, v[38:39]
	s_mov_b32 s41, s12
	v_lshl_add_u64 v[38:39], s[40:41], 2, v[38:39]
	v_lshlrev_b32_e32 v144, 2, v2
	v_lshl_add_u64 v[38:39], v[38:39], 0, v[144:145]
	s_movk_i32 s4, 0x4000
	v_add_co_u32_e32 v40, vcc, s4, v38
	s_mov_b32 s4, 0x8000
	s_nop 0
	v_addc_co_u32_e32 v41, vcc, 0, v39, vcc
	v_add_co_u32_e32 v42, vcc, s4, v38
	s_mov_b32 s4, 0xc000
	s_nop 0
	v_addc_co_u32_e32 v43, vcc, 0, v39, vcc
	v_add_co_u32_e32 v44, vcc, s4, v38
	s_mov_b32 s4, 0x14000
	s_nop 0
	v_addc_co_u32_e32 v45, vcc, 0, v39, vcc
	v_add_co_u32_e32 v46, vcc, s52, v38
	s_lshl_b32 s28, s7, 1
	s_nop 0
	v_addc_co_u32_e32 v47, vcc, 0, v39, vcc
	s_waitcnt vmcnt(0)
	v_add_co_u32_e32 v48, vcc, s4, v38
	s_mov_b32 s4, 0x18000
	s_nop 0
	v_addc_co_u32_e32 v49, vcc, 0, v39, vcc
	v_add_co_u32_e32 v50, vcc, s4, v38
	s_mov_b32 s4, 0x1c000
	s_nop 0
	v_addc_co_u32_e32 v51, vcc, 0, v39, vcc
	v_add_co_u32_e32 v52, vcc, s4, v38
	s_mov_b32 s4, 0x20000
	s_nop 0
	v_addc_co_u32_e32 v53, vcc, 0, v39, vcc
	global_load_dword v56, v[38:39], off nt
	global_load_dword v57, v[40:41], off nt
	global_load_dword v59, v[42:43], off nt
	global_load_dword v60, v[44:45], off nt
	global_load_dword v61, v[46:47], off nt
	global_load_dword v62, v[48:49], off nt
	global_load_dword v63, v[50:51], off nt
	global_load_dword v64, v[52:53], off nt
	v_add_co_u32_e32 v40, vcc, s4, v38
	s_mov_b32 s4, 0x24000
	s_nop 0
	v_addc_co_u32_e32 v41, vcc, 0, v39, vcc
	v_add_co_u32_e32 v42, vcc, s4, v38
	s_mov_b32 s4, 0x28000
	s_nop 0
	v_addc_co_u32_e32 v43, vcc, 0, v39, vcc
	v_add_co_u32_e32 v44, vcc, s4, v38
	s_mov_b32 s4, 0x2c000
	s_nop 0
	v_addc_co_u32_e32 v45, vcc, 0, v39, vcc
	v_add_co_u32_e32 v46, vcc, s4, v38
	s_mov_b32 s4, 0x30000
	s_nop 0
	v_addc_co_u32_e32 v47, vcc, 0, v39, vcc
	v_add_co_u32_e32 v48, vcc, s4, v38
	s_mov_b32 s4, 0x34000
	s_nop 0
	v_addc_co_u32_e32 v49, vcc, 0, v39, vcc
	v_add_co_u32_e32 v50, vcc, s4, v38
	s_mov_b32 s4, 0x38000
	s_nop 0
	v_addc_co_u32_e32 v51, vcc, 0, v39, vcc
	v_add_co_u32_e32 v52, vcc, s4, v38
	s_mov_b32 s4, 0x3c000
	s_nop 0
	v_addc_co_u32_e32 v53, vcc, 0, v39, vcc
	v_add_co_u32_e32 v54, vcc, s4, v38
	s_mov_b32 s4, 0x40000
	s_nop 0
	v_addc_co_u32_e32 v55, vcc, 0, v39, vcc
	global_load_dword v65, v[40:41], off nt
	global_load_dword v66, v[42:43], off nt
	global_load_dword v67, v[44:45], off nt
	global_load_dword v68, v[46:47], off nt
	global_load_dword v69, v[48:49], off nt
	global_load_dword v70, v[50:51], off nt
	global_load_dword v71, v[52:53], off nt
	global_load_dword v72, v[54:55], off nt
	v_add_co_u32_e32 v40, vcc, s4, v38
	s_mov_b32 s4, 0x44000
	s_nop 0
	v_addc_co_u32_e32 v41, vcc, 0, v39, vcc
	v_add_co_u32_e32 v42, vcc, s4, v38
	s_mov_b32 s4, 0x48000
	s_nop 0
	v_addc_co_u32_e32 v43, vcc, 0, v39, vcc
	v_add_co_u32_e32 v44, vcc, s4, v38
	s_mov_b32 s4, 0x4c000
	s_nop 0
	v_addc_co_u32_e32 v45, vcc, 0, v39, vcc
	v_add_co_u32_e32 v46, vcc, s4, v38
	s_mov_b32 s4, 0x50000
	s_nop 0
	v_addc_co_u32_e32 v47, vcc, 0, v39, vcc
	v_add_co_u32_e32 v48, vcc, s4, v38
	s_mov_b32 s4, 0x54000
	s_nop 0
	v_addc_co_u32_e32 v49, vcc, 0, v39, vcc
	v_add_co_u32_e32 v50, vcc, s4, v38
	s_mov_b32 s4, 0x58000
	s_nop 0
	v_addc_co_u32_e32 v51, vcc, 0, v39, vcc
	v_add_co_u32_e32 v52, vcc, s4, v38
	s_mov_b32 s4, 0x5c000
	s_nop 0
	v_addc_co_u32_e32 v53, vcc, 0, v39, vcc
	v_add_co_u32_e32 v54, vcc, s4, v38
	s_mov_b32 s4, 0x60000
	s_nop 0
	v_addc_co_u32_e32 v55, vcc, 0, v39, vcc
	global_load_dword v73, v[40:41], off nt
	global_load_dword v74, v[42:43], off nt
	global_load_dword v75, v[44:45], off nt
	global_load_dword v76, v[46:47], off nt
	global_load_dword v77, v[48:49], off nt
	global_load_dword v78, v[50:51], off nt
	global_load_dword v79, v[52:53], off nt
	s_nop 0
	global_load_dword v54, v[54:55], off nt
	v_add_co_u32_e32 v40, vcc, s4, v38
	s_mov_b32 s4, 0x64000
	s_nop 0
	v_addc_co_u32_e32 v41, vcc, 0, v39, vcc
	v_add_co_u32_e32 v42, vcc, s4, v38
	s_mov_b32 s4, 0x68000
	s_nop 0
	v_addc_co_u32_e32 v43, vcc, 0, v39, vcc
	v_add_co_u32_e32 v44, vcc, s4, v38
	s_mov_b32 s4, 0x6c000
	s_nop 0
	v_addc_co_u32_e32 v45, vcc, 0, v39, vcc
	v_add_co_u32_e32 v46, vcc, s4, v38
	s_mov_b32 s4, 0x70000
	s_nop 0
	v_addc_co_u32_e32 v47, vcc, 0, v39, vcc
	v_add_co_u32_e32 v48, vcc, s4, v38
	s_mov_b32 s4, 0x74000
	s_nop 0
	v_addc_co_u32_e32 v49, vcc, 0, v39, vcc
	v_add_co_u32_e32 v50, vcc, s4, v38
	s_mov_b32 s4, 0x78000
	s_nop 0
	v_addc_co_u32_e32 v51, vcc, 0, v39, vcc
	v_add_co_u32_e32 v52, vcc, s4, v38
	s_mov_b32 s4, 0x7c000
	s_nop 0
	v_addc_co_u32_e32 v53, vcc, 0, v39, vcc
	v_add_co_u32_e32 v38, vcc, s4, v38
	s_mov_b32 s29, s12
	s_nop 0
	v_addc_co_u32_e32 v39, vcc, 0, v39, vcc
	global_load_dword v40, v[40:41], off nt
	s_nop 0
	global_load_dword v41, v[42:43], off nt
	s_nop 0
	global_load_dword v42, v[44:45], off nt
	global_load_dword v43, v[46:47], off nt
	s_nop 0
	global_load_dword v44, v[48:49], off nt
	global_load_dword v45, v[50:51], off nt
	global_load_dword v46, v[52:53], off nt
	s_nop 0
	global_load_dword v38, v[38:39], off nt
	v_add_u32_e32 v39, 0x400, v6
	s_waitcnt vmcnt(0)
; #define LAS __attribute__((address_space(3)))
; __device__ __forceinline__ unsigned cvt_pk_bf16(float lo, float hi) { unsigned r; asm volatile("v_cvt_pk_bf16_f32 %0, %1, %2" : "=v"(r) : "v"(lo), "v"(hi)); return r; }
; #define LDS_WAIT() asm volatile("s_waitcnt lgkmcnt(0)" ::: "memory")
; __device__ __forceinline__ void tr_item(const float* __restrict__ W, int K, int N, bf16_t* __restrict__ WT, int dst_row0, int src_col0, int k0, LAS float* scr, int lane) {
;     ...
;         for (int i = 0; i < 32; ++i) scr[(2 * i + (lane >> 5)) * 33 + (lane & 31)] = t[i];
;     } else {
; #pragma unroll 8
;         for (int i = 0; i < 32; ++i) { const int kk = 2 * i + (lane >> 5); scr[kk * 33 + (lane & 31)] = 0.f; }
;     }
;     LDS_WAIT(); asm volatile("" ::: "memory");
;     const int c = lane & 7;
; #pragma unroll
;     for (int j = 0; j < 4; ++j) { const int n = (lane >> 3) + 8 * j; const LAS float* s = scr + (8 * c) * 33 + n;
;         u32x4 o; o.x = cvt_pk_bf16(s[0 * 33], s[1 * 33]); o.y = cvt_pk_bf16(s[2 * 33], s[3 * 33]); o.z = cvt_pk_bf16(s[4 * 33], s[5 * 33]); o.w = cvt_pk_bf16(s[6 * 33], s[7 * 33]);
;         *(u32x4*)(WT + (size_t)(dst_row0 + n) * K + k0 + 8 * c) = o; }
;     LDS_WAIT(); asm volatile("" ::: "memory");
	ds_write2_b32 v6, v56, v57 offset1:66
	ds_write2_b32 v6, v59, v60 offset0:132 offset1:198
	ds_write2_b32 v39, v61, v62 offset0:8 offset1:74
	ds_write2_b32 v39, v63, v64 offset0:140 offset1:206
	v_add_u32_e32 v39, 0x800, v6
	ds_write2_b32 v39, v65, v66 offset0:16 offset1:82
	ds_write2_b32 v39, v67, v68 offset0:148 offset1:214
	v_add_u32_e32 v39, 0xc00, v6
	ds_write2_b32 v39, v69, v70 offset0:24 offset1:90
	ds_write2_b32 v39, v71, v72 offset0:156 offset1:222
	v_add_u32_e32 v39, 0x1000, v6
	ds_write2_b32 v39, v73, v74 offset0:32 offset1:98
	ds_write2_b32 v39, v75, v76 offset0:164 offset1:230
	v_add_u32_e32 v39, 0x1400, v6
	ds_write2_b32 v39, v77, v78 offset0:40 offset1:106
	ds_write2_b32 v39, v79, v54 offset0:172 offset1:238
	v_add_u32_e32 v39, 0x1800, v6
	ds_write2_b32 v39, v40, v41 offset0:48 offset1:114
	ds_write2_b32 v39, v42, v43 offset0:180 offset1:246
	v_add_u32_e32 v39, 0x1c00, v6
	ds_write2_b32 v39, v44, v45 offset0:56 offset1:122
	ds_write2_b32 v39, v46, v38 offset0:188 offset1:254
	s_waitcnt lgkmcnt(0)
	ds_read2_b32 v[56:57], v33 offset1:33
	ds_read2_b32 v[60:61], v33 offset0:66 offset1:99
	ds_read2_b32 v[62:63], v33 offset0:132 offset1:165
	ds_read2_b32 v[64:65], v33 offset0:198 offset1:231
	ds_read2_b32 v[66:67], v33 offset0:8 offset1:41
	ds_read2_b32 v[68:69], v33 offset0:74 offset1:107
	ds_read2_b32 v[70:71], v33 offset0:140 offset1:173
	ds_read2_b32 v[72:73], v33 offset0:206 offset1:239
	s_waitcnt lgkmcnt(7)
	v_cvt_pk_bf16_f32 v38, v56, v57
	s_waitcnt lgkmcnt(6)
	v_cvt_pk_bf16_f32 v39, v60, v61
	s_waitcnt lgkmcnt(5)
	v_cvt_pk_bf16_f32 v40, v62, v63
	s_waitcnt lgkmcnt(4)
	v_cvt_pk_bf16_f32 v41, v64, v65
	v_add_u32_e32 v42, s40, v31
	v_ashrrev_i32_e32 v43, 31, v42
	v_lshl_add_u64 v[44:45], v[20:21], 0, s[28:29]
	v_lshlrev_b64 v[42:43], 12, v[42:43]
	v_lshl_add_u64 v[42:43], v[44:45], 0, v[42:43]
	global_store_dwordx4 v[42:43], v[38:41], off
	s_nop 1
	s_waitcnt lgkmcnt(3)
	s_nop 0
	v_cvt_pk_bf16_f32 v38, v66, v67
	s_waitcnt lgkmcnt(2)
	v_cvt_pk_bf16_f32 v39, v68, v69
	s_waitcnt lgkmcnt(1)
	v_cvt_pk_bf16_f32 v40, v70, v71
	s_waitcnt lgkmcnt(0)
	v_cvt_pk_bf16_f32 v41, v72, v73
	v_add_u32_e32 v42, s40, v35
	v_ashrrev_i32_e32 v43, 31, v42
	v_lshlrev_b64 v[42:43], 12, v[42:43]
	v_lshl_add_u64 v[42:43], v[44:45], 0, v[42:43]
	ds_read2_b32 v[56:57], v33 offset0:16 offset1:49
	ds_read2_b32 v[60:61], v33 offset0:82 offset1:115
	ds_read2_b32 v[62:63], v33 offset0:148 offset1:181
	ds_read2_b32 v[64:65], v33 offset0:214 offset1:247
	ds_read2_b32 v[66:67], v33 offset0:24 offset1:57
	ds_read2_b32 v[68:69], v33 offset0:90 offset1:123
	ds_read2_b32 v[70:71], v33 offset0:156 offset1:189
	ds_read2_b32 v[72:73], v33 offset0:222 offset1:255
	global_store_dwordx4 v[42:43], v[38:41], off
	s_nop 1
	s_waitcnt lgkmcnt(7)
	s_nop 0
	v_cvt_pk_bf16_f32 v38, v56, v57
	s_waitcnt lgkmcnt(6)
	v_cvt_pk_bf16_f32 v39, v60, v61
	s_waitcnt lgkmcnt(5)
	v_cvt_pk_bf16_f32 v40, v62, v63
	s_waitcnt lgkmcnt(4)
	v_cvt_pk_bf16_f32 v41, v64, v65
	v_add_u32_e32 v42, s40, v36
	v_ashrrev_i32_e32 v43, 31, v42
	v_lshlrev_b64 v[42:43], 12, v[42:43]
	v_lshl_add_u64 v[42:43], v[44:45], 0, v[42:43]
	global_store_dwordx4 v[42:43], v[38:41], off
	s_nop 1
	s_waitcnt lgkmcnt(3)
	s_nop 0
	v_cvt_pk_bf16_f32 v38, v66, v67
	s_waitcnt lgkmcnt(2)
	v_cvt_pk_bf16_f32 v39, v68, v69
	s_waitcnt lgkmcnt(1)
	v_cvt_pk_bf16_f32 v40, v70, v71
	s_waitcnt lgkmcnt(0)
	v_cvt_pk_bf16_f32 v41, v72, v73
	v_add_u32_e32 v42, s40, v37
	v_ashrrev_i32_e32 v43, 31, v42
	v_lshlrev_b64 v[42:43], 12, v[42:43]
	v_lshl_add_u64 v[42:43], v[44:45], 0, v[42:43]
	global_store_dwordx4 v[42:43], v[38:41], off
	s_nop 1
	s_waitcnt lgkmcnt(0)

; #define LAS __attribute__((address_space(3)))
; __device__ __forceinline__ void tr_item(const float* __restrict__ W, int K, int N, bf16_t* __restrict__ WT, int dst_row0, int src_col0, int k0, LAS float* scr, int lane) {
;     if (src_col0 >= 0) {
;         const float* wp = W + (size_t)(k0 + (lane >> 5)) * N + src_col0 + (lane & 31);
;         float t[32];
; #pragma unroll
;         for (int i = 0; i < 32; ++i) t[i] = __builtin_nontemporal_load(wp + (size_t)(2 * i) * N);
.LBB0_928:
	s_and_b32 s18, s7, 0x3c0
	v_add_u32_e32 v38, s18, v0
	s_lshl_b32 s13, s7, 5
	v_ashrrev_i32_e32 v39, 31, v38
	s_and_b32 s13, s13, 0x7e0
	v_lshlrev_b64 v[38:39], 13, v[38:39]
	v_lshl_add_u64 v[38:39], s[36:37], 0, v[38:39]
	s_lshl_b32 s28, s13, 2
	s_mov_b32 s29, s12
	v_lshl_add_u64 v[38:39], v[38:39], 0, s[28:29]
	v_lshlrev_b32_e32 v144, 2, v2
	v_lshl_add_u64 v[38:39], v[38:39], 0, v[144:145]
	s_movk_i32 s4, 0x4000
	v_add_co_u32_e32 v40, vcc, s4, v38
	s_mov_b32 s4, 0x8000
	s_nop 0
	v_addc_co_u32_e32 v41, vcc, 0, v39, vcc
	v_add_co_u32_e32 v42, vcc, s4, v38
	s_mov_b32 s4, 0xc000
	s_nop 0
	v_addc_co_u32_e32 v43, vcc, 0, v39, vcc
	v_add_co_u32_e32 v44, vcc, s4, v38
	s_mov_b32 s4, 0x14000
	s_nop 0
	v_addc_co_u32_e32 v45, vcc, 0, v39, vcc
	v_add_co_u32_e32 v46, vcc, s52, v38
	s_lshl_b32 s28, s18, 1
	s_nop 0
	v_addc_co_u32_e32 v47, vcc, 0, v39, vcc
	s_waitcnt vmcnt(0)
	v_add_co_u32_e32 v48, vcc, s4, v38
	s_mov_b32 s4, 0x18000
	s_nop 0
	v_addc_co_u32_e32 v49, vcc, 0, v39, vcc
	v_add_co_u32_e32 v50, vcc, s4, v38
	s_mov_b32 s4, 0x1c000
	s_nop 0
	v_addc_co_u32_e32 v51, vcc, 0, v39, vcc
	v_add_co_u32_e32 v52, vcc, s4, v38
	s_mov_b32 s4, 0x20000
	s_nop 0
	v_addc_co_u32_e32 v53, vcc, 0, v39, vcc
	global_load_dword v56, v[38:39], off nt
	global_load_dword v57, v[40:41], off nt
	global_load_dword v59, v[42:43], off nt
	global_load_dword v60, v[44:45], off nt
	global_load_dword v61, v[46:47], off nt
	global_load_dword v62, v[48:49], off nt
	global_load_dword v63, v[50:51], off nt
	global_load_dword v64, v[52:53], off nt
	v_add_co_u32_e32 v40, vcc, s4, v38
	s_mov_b32 s4, 0x24000
	s_nop 0
	v_addc_co_u32_e32 v41, vcc, 0, v39, vcc
	v_add_co_u32_e32 v42, vcc, s4, v38
	s_mov_b32 s4, 0x28000
	s_nop 0
	v_addc_co_u32_e32 v43, vcc, 0, v39, vcc
	v_add_co_u32_e32 v44, vcc, s4, v38
	s_mov_b32 s4, 0x2c000
	s_nop 0
	v_addc_co_u32_e32 v45, vcc, 0, v39, vcc
	v_add_co_u32_e32 v46, vcc, s4, v38
	s_mov_b32 s4, 0x30000
	s_nop 0
	v_addc_co_u32_e32 v47, vcc, 0, v39, vcc
	v_add_co_u32_e32 v48, vcc, s4, v38
	s_mov_b32 s4, 0x34000
	s_nop 0
	v_addc_co_u32_e32 v49, vcc, 0, v39, vcc
	v_add_co_u32_e32 v50, vcc, s4, v38
	s_mov_b32 s4, 0x38000
	s_nop 0
	v_addc_co_u32_e32 v51, vcc, 0, v39, vcc
	v_add_co_u32_e32 v52, vcc, s4, v38
	s_mov_b32 s4, 0x3c000
	s_nop 0
	v_addc_co_u32_e32 v53, vcc, 0, v39, vcc
	v_add_co_u32_e32 v54, vcc, s4, v38
	s_mov_b32 s4, 0x40000
	s_nop 0
	v_addc_co_u32_e32 v55, vcc, 0, v39, vcc
	global_load_dword v65, v[40:41], off nt
	global_load_dword v66, v[42:43], off nt
	global_load_dword v67, v[44:45], off nt
	global_load_dword v68, v[46:47], off nt
	global_load_dword v69, v[48:49], off nt
	global_load_dword v70, v[50:51], off nt
	global_load_dword v71, v[52:53], off nt
	global_load_dword v72, v[54:55], off nt
	v_add_co_u32_e32 v40, vcc, s4, v38
	s_mov_b32 s4, 0x44000
	s_nop 0
	v_addc_co_u32_e32 v41, vcc, 0, v39, vcc
	v_add_co_u32_e32 v42, vcc, s4, v38
	s_mov_b32 s4, 0x48000
	s_nop 0
	v_addc_co_u32_e32 v43, vcc, 0, v39, vcc
	v_add_co_u32_e32 v44, vcc, s4, v38
	s_mov_b32 s4, 0x4c000
	s_nop 0
	v_addc_co_u32_e32 v45, vcc, 0, v39, vcc
	v_add_co_u32_e32 v46, vcc, s4, v38
	s_mov_b32 s4, 0x50000
	s_nop 0
	v_addc_co_u32_e32 v47, vcc, 0, v39, vcc
	v_add_co_u32_e32 v48, vcc, s4, v38
	s_mov_b32 s4, 0x54000
	s_nop 0
	v_addc_co_u32_e32 v49, vcc, 0, v39, vcc
	v_add_co_u32_e32 v50, vcc, s4, v38
	s_mov_b32 s4, 0x58000
	s_nop 0
	v_addc_co_u32_e32 v51, vcc, 0, v39, vcc
	v_add_co_u32_e32 v52, vcc, s4, v38
	s_mov_b32 s4, 0x5c000
	s_nop 0
	v_addc_co_u32_e32 v53, vcc, 0, v39, vcc
	v_add_co_u32_e32 v54, vcc, s4, v38
	s_mov_b32 s4, 0x60000
	s_nop 0
	v_addc_co_u32_e32 v55, vcc, 0, v39, vcc
	global_load_dword v73, v[40:41], off nt
	global_load_dword v74, v[42:43], off nt
	global_load_dword v75, v[44:45], off nt
	global_load_dword v76, v[46:47], off nt
	global_load_dword v77, v[48:49], off nt
	global_load_dword v78, v[50:51], off nt
	global_load_dword v79, v[52:53], off nt
	s_nop 0
	global_load_dword v54, v[54:55], off nt
	v_add_co_u32_e32 v40, vcc, s4, v38
	s_mov_b32 s4, 0x64000
	s_nop 0
	v_addc_co_u32_e32 v41, vcc, 0, v39, vcc
	v_add_co_u32_e32 v42, vcc, s4, v38
	s_mov_b32 s4, 0x68000
	s_nop 0
	v_addc_co_u32_e32 v43, vcc, 0, v39, vcc
	v_add_co_u32_e32 v44, vcc, s4, v38
	s_mov_b32 s4, 0x6c000
	s_nop 0
	v_addc_co_u32_e32 v45, vcc, 0, v39, vcc
	v_add_co_u32_e32 v46, vcc, s4, v38
	s_mov_b32 s4, 0x70000
	s_nop 0
	v_addc_co_u32_e32 v47, vcc, 0, v39, vcc
	v_add_co_u32_e32 v48, vcc, s4, v38
	s_mov_b32 s4, 0x74000
	s_nop 0
	v_addc_co_u32_e32 v49, vcc, 0, v39, vcc
	v_add_co_u32_e32 v50, vcc, s4, v38
	s_mov_b32 s4, 0x78000
	s_nop 0
	v_addc_co_u32_e32 v51, vcc, 0, v39, vcc
	v_add_co_u32_e32 v52, vcc, s4, v38
	s_mov_b32 s4, 0x7c000
	s_nop 0
	v_addc_co_u32_e32 v53, vcc, 0, v39, vcc
	v_add_co_u32_e32 v38, vcc, s4, v38
	s_nop 1
	v_addc_co_u32_e32 v39, vcc, 0, v39, vcc
	global_load_dword v40, v[40:41], off nt
	s_nop 0
	global_load_dword v41, v[42:43], off nt
	s_nop 0
	global_load_dword v42, v[44:45], off nt
	global_load_dword v43, v[46:47], off nt
	s_nop 0
	global_load_dword v44, v[48:49], off nt
	global_load_dword v45, v[50:51], off nt
	global_load_dword v46, v[52:53], off nt
	s_nop 0
	global_load_dword v38, v[38:39], off nt
	v_add_u32_e32 v39, 0x400, v6
	s_waitcnt vmcnt(0)
; #define LAS __attribute__((address_space(3)))
; __device__ __forceinline__ unsigned cvt_pk_bf16(float lo, float hi) { unsigned r; asm volatile("v_cvt_pk_bf16_f32 %0, %1, %2" : "=v"(r) : "v"(lo), "v"(hi)); return r; }
; #define LDS_WAIT() asm volatile("s_waitcnt lgkmcnt(0)" ::: "memory")
; __device__ __forceinline__ void tr_item(const float* __restrict__ W, int K, int N, bf16_t* __restrict__ WT, int dst_row0, int src_col0, int k0, LAS float* scr, int lane) {
;     ...
;         for (int i = 0; i < 32; ++i) scr[(2 * i + (lane >> 5)) * 33 + (lane & 31)] = t[i];
;     } else {
; #pragma unroll 8
;         for (int i = 0; i < 32; ++i) { const int kk = 2 * i + (lane >> 5); scr[kk * 33 + (lane & 31)] = 0.f; }
;     }
;     LDS_WAIT(); asm volatile("" ::: "memory");
;     const int c = lane & 7;
; #pragma unroll
;     for (int j = 0; j < 4; ++j) { const int n = (lane >> 3) + 8 * j; const LAS float* s = scr + (8 * c) * 33 + n;
;         u32x4 o; o.x = cvt_pk_bf16(s[0 * 33], s[1 * 33]); o.y = cvt_pk_bf16(s[2 * 33], s[3 * 33]); o.z = cvt_pk_bf16(s[4 * 33], s[5 * 33]); o.w = cvt_pk_bf16(s[6 * 33], s[7 * 33]);
;         *(u32x4*)(WT + (size_t)(dst_row0 + n) * K + k0 + 8 * c) = o; }
;     LDS_WAIT(); asm volatile("" ::: "memory");
	ds_write2_b32 v6, v56, v57 offset1:66
	ds_write2_b32 v6, v59, v60 offset0:132 offset1:198
	ds_write2_b32 v39, v61, v62 offset0:8 offset1:74
	ds_write2_b32 v39, v63, v64 offset0:140 offset1:206
	v_add_u32_e32 v39, 0x800, v6
	ds_write2_b32 v39, v65, v66 offset0:16 offset1:82
	ds_write2_b32 v39, v67, v68 offset0:148 offset1:214
	v_add_u32_e32 v39, 0xc00, v6
	ds_write2_b32 v39, v69, v70 offset0:24 offset1:90
	ds_write2_b32 v39, v71, v72 offset0:156 offset1:222
	v_add_u32_e32 v39, 0x1000, v6
	ds_write2_b32 v39, v73, v74 offset0:32 offset1:98
	ds_write2_b32 v39, v75, v76 offset0:164 offset1:230
	v_add_u32_e32 v39, 0x1400, v6
	ds_write2_b32 v39, v77, v78 offset0:40 offset1:106
	ds_write2_b32 v39, v79, v54 offset0:172 offset1:238
	v_add_u32_e32 v39, 0x1800, v6
	ds_write2_b32 v39, v40, v41 offset0:48 offset1:114
	ds_write2_b32 v39, v42, v43 offset0:180 offset1:246
	v_add_u32_e32 v39, 0x1c00, v6
	ds_write2_b32 v39, v44, v45 offset0:56 offset1:122
	ds_write2_b32 v39, v46, v38 offset0:188 offset1:254
	s_waitcnt lgkmcnt(0)
	ds_read2_b32 v[56:57], v33 offset1:33
	ds_read2_b32 v[60:61], v33 offset0:66 offset1:99
	ds_read2_b32 v[62:63], v33 offset0:132 offset1:165
	ds_read2_b32 v[64:65], v33 offset0:198 offset1:231
	ds_read2_b32 v[66:67], v33 offset0:8 offset1:41
	ds_read2_b32 v[68:69], v33 offset0:74 offset1:107
	ds_read2_b32 v[70:71], v33 offset0:140 offset1:173
	ds_read2_b32 v[72:73], v33 offset0:206 offset1:239
	s_waitcnt lgkmcnt(7)
	v_cvt_pk_bf16_f32 v38, v56, v57
	s_waitcnt lgkmcnt(6)
	v_cvt_pk_bf16_f32 v39, v60, v61
	s_waitcnt lgkmcnt(5)
	v_cvt_pk_bf16_f32 v40, v62, v63
	s_waitcnt lgkmcnt(4)
	v_cvt_pk_bf16_f32 v41, v64, v65
	v_add_u32_e32 v42, s13, v31
	v_ashrrev_i32_e32 v43, 31, v42
	v_lshl_add_u64 v[44:45], v[18:19], 0, s[28:29]
	v_lshlrev_b64 v[42:43], 11, v[42:43]
	v_lshl_add_u64 v[42:43], v[44:45], 0, v[42:43]
	global_store_dwordx4 v[42:43], v[38:41], off
	s_nop 1
	s_waitcnt lgkmcnt(3)
	s_nop 0
	v_cvt_pk_bf16_f32 v38, v66, v67
	s_waitcnt lgkmcnt(2)
	v_cvt_pk_bf16_f32 v39, v68, v69
	s_waitcnt lgkmcnt(1)
	v_cvt_pk_bf16_f32 v40, v70, v71
	s_waitcnt lgkmcnt(0)
	v_cvt_pk_bf16_f32 v41, v72, v73
	v_add_u32_e32 v42, s13, v35
	v_ashrrev_i32_e32 v43, 31, v42
	v_lshlrev_b64 v[42:43], 11, v[42:43]
	v_lshl_add_u64 v[42:43], v[44:45], 0, v[42:43]
	ds_read2_b32 v[56:57], v33 offset0:16 offset1:49
	ds_read2_b32 v[60:61], v33 offset0:82 offset1:115
	ds_read2_b32 v[62:63], v33 offset0:148 offset1:181
	ds_read2_b32 v[64:65], v33 offset0:214 offset1:247
	ds_read2_b32 v[66:67], v33 offset0:24 offset1:57
	ds_read2_b32 v[68:69], v33 offset0:90 offset1:123
	ds_read2_b32 v[70:71], v33 offset0:156 offset1:189
	ds_read2_b32 v[72:73], v33 offset0:222 offset1:255
	global_store_dwordx4 v[42:43], v[38:41], off
	s_nop 1
	s_waitcnt lgkmcnt(7)
	s_nop 0
	v_cvt_pk_bf16_f32 v38, v56, v57
	s_waitcnt lgkmcnt(6)
	v_cvt_pk_bf16_f32 v39, v60, v61
	s_waitcnt lgkmcnt(5)
	v_cvt_pk_bf16_f32 v40, v62, v63
	s_waitcnt lgkmcnt(4)
	v_cvt_pk_bf16_f32 v41, v64, v65
	v_add_u32_e32 v42, s13, v36
	v_ashrrev_i32_e32 v43, 31, v42
	v_lshlrev_b64 v[42:43], 11, v[42:43]
	v_lshl_add_u64 v[42:43], v[44:45], 0, v[42:43]
	global_store_dwordx4 v[42:43], v[38:41], off
	s_nop 1
	s_waitcnt lgkmcnt(3)
	s_nop 0
	v_cvt_pk_bf16_f32 v38, v66, v67
	s_waitcnt lgkmcnt(2)
	v_cvt_pk_bf16_f32 v39, v68, v69
	s_waitcnt lgkmcnt(1)
	v_cvt_pk_bf16_f32 v40, v70, v71
	s_waitcnt lgkmcnt(0)
	v_cvt_pk_bf16_f32 v41, v72, v73
	v_add_u32_e32 v42, s13, v37
	v_ashrrev_i32_e32 v43, 31, v42
	v_lshlrev_b64 v[42:43], 11, v[42:43]
	v_lshl_add_u64 v[42:43], v[44:45], 0, v[42:43]
	global_store_dwordx4 v[42:43], v[38:41], off
	s_nop 1
	s_waitcnt lgkmcnt(0)
	s_mov_b32 s13, s7
	s_andn2_b64 vcc, exec, s[40:41]
	s_cbranch_vccz .LBB0_910
	s_branch .LBB0_911
